# adds: interleaved DMA/LDS-read issue in K-loops, per-tile store drain deferred (vmcnt 16), scan state stores widened to dwordx4 via permlane16_swap
# speedup vs baseline: 1.0128x; 1.0128x over previous
; #define PG8_STAGE(bufoff, gbase, voff) do { _Pragma("unroll") for (int _i = 0; _i < 2; ++_i) \
;         __builtin_amdgcn_global_load_lds((const unsigned*)((const char*)(gbase) + (voff)[_i]), (LAS unsigned*)(lds + (bufoff) + ldsw + _i * 8192), 16, 0, 0); } while (0)
; #define PG8_LDA(dst, b, h) do { _Pragma("unroll") for (int m = 0; m < 4; ++m) _Pragma("unroll") for (int k = 0; k < 2; ++k) dst[m][k] = *(const LAS bf16x8*)(lds + PG8_SA(b, h) + aoff + m * 2048 + k * 1024); } while (0)
; #define PG8_WAIT_V(n) asm volatile("s_waitcnt vmcnt(" #n ")" ::: "memory")
; #define PG8_WAIT_L(n) asm volatile("s_waitcnt lgkmcnt(" #n ")" ::: "memory")
; template <class Prog>
; __device__ __forceinline__ void gemm_phase(LAS unsigned char* lds, const int K, const Prog& S) {
;     ...
;     Unit cur, nxt; int ui = 0;
;     if (!S.next(0, cur)) return;
;     f32x4 acc[2][2][4][2];
; #pragma unroll
;     for (int a = 0; a < 2; ++a)
; #pragma unroll
;         for (int b = 0; b < 2; ++b)
; #pragma unroll
;             for (int m = 0; m < 4; ++m)
; #pragma unroll
;                 for (int n = 0; n < 2; ++n) acc[a][b][m][n] = (f32x4){0.f, 0.f, 0.f, 0.f};
;     bf16x8 At[4][2], B0[2][2], B1[2][2];
;     const char* cA = cur.a; const char* cB = cur.b;
;     PG8_STAGE(PG8_SB(0, 0), cB, voffB); PG8_STAGE(PG8_SA(0, 0), cA, voffA); PG8_STAGE(PG8_SB(0, 1), cB + hstep, voffB); PG8_STAGE(PG8_SA(0, 1), cA + hstep, voffA);
;     if (wr == 1) PG8_BAR;
;     PG8_WAIT_V(4); PG8_BAR;
;     PG8_STAGE(PG8_SB(1, 0), cB + kstep, voffB); PG8_STAGE(PG8_SA(1, 0), cA + kstep, voffA); PG8_STAGE(PG8_SB(1, 1), cB + hstep + kstep, voffB);
;     PG8_WAIT_V(6); PG8_BAR;
;     for (;;) {
;         const bool has_next = S.next(ui + 1, nxt);
;         const char* nA = has_next ? nxt.a : cA; const char* nB = has_next ? nxt.b : cB;
;         for (int t = 0; t < nt; t += 2) {
;             const bool last = (t == nt - 2);
;             const char* a1 = cA + (size_t)(t + 1) * kstep;
;             const char* a2 = last ? nA : cA + (size_t)(t + 2) * kstep; const char* b2 = last ? nB : cB + (size_t)(t + 2) * kstep;
;             const char* a3 = a2 + kstep; const char* b3 = b2 + kstep;
;             PG8_LDB(B0, 0, 0); PG8_SCHED; PG8_LDA(At, 0, 0); PG8_STAGE(PG8_SA(1, 1), a1 + hstep, voffA);
;             PG8_WAIT_L(8); PG8_BAR; PG8_WAIT_L(0); PG8_MMA(0, 0, At, B0); PG8_BAR; PG8_SCHED;
.LBB0_100:
	s_add_u32 s40, s40, 0x80080
	s_addc_u32 s41, s41, 0
	s_add_u32 s9, s44, 0x100
	v_mov_b32_e32 v0, 0
	s_addc_u32 s15, s45, 0
	s_mov_b32 s69, -2
	v_mov_b32_e32 v1, v0
	v_mov_b32_e32 v2, v0
	v_mov_b32_e32 v3, v0
	v_mov_b32_e32 v8, v0
	v_mov_b32_e32 v9, v0
	v_mov_b32_e32 v10, v0
	v_mov_b32_e32 v11, v0
	v_mov_b32_e32 v16, v0
	v_mov_b32_e32 v17, v0
	v_mov_b32_e32 v18, v0
	v_mov_b32_e32 v19, v0
	s_waitcnt vmcnt(16)
	v_mov_b32_e32 v24, v0
	v_mov_b32_e32 v25, v0
	v_mov_b32_e32 v26, v0
	v_mov_b32_e32 v27, v0
	v_mov_b32_e32 v32, v0
	v_mov_b32_e32 v33, v0
	v_mov_b32_e32 v34, v0
	v_mov_b32_e32 v35, v0
	v_mov_b32_e32 v40, v0
	v_mov_b32_e32 v41, v0
	v_mov_b32_e32 v42, v0
	v_mov_b32_e32 v43, v0
	v_mov_b32_e32 v48, v0
	v_mov_b32_e32 v49, v0
	v_mov_b32_e32 v50, v0
	v_mov_b32_e32 v51, v0
	v_mov_b32_e32 v56, v0
	v_mov_b32_e32 v57, v0
	v_mov_b32_e32 v58, v0
	v_mov_b32_e32 v59, v0
	v_mov_b32_e32 v4, v0
	v_mov_b32_e32 v5, v0
	v_mov_b32_e32 v6, v0
	v_mov_b32_e32 v7, v0
	v_mov_b32_e32 v12, v0
	v_mov_b32_e32 v13, v0
	v_mov_b32_e32 v14, v0
	v_mov_b32_e32 v15, v0
	v_mov_b32_e32 v20, v0
	v_mov_b32_e32 v21, v0
	v_mov_b32_e32 v22, v0
	v_mov_b32_e32 v23, v0
	v_mov_b32_e32 v28, v0
	v_mov_b32_e32 v29, v0
	v_mov_b32_e32 v30, v0
	v_mov_b32_e32 v31, v0
	v_mov_b32_e32 v36, v0
	v_mov_b32_e32 v37, v0
	v_mov_b32_e32 v38, v0
	v_mov_b32_e32 v39, v0
	v_mov_b32_e32 v44, v0
	v_mov_b32_e32 v45, v0
	v_mov_b32_e32 v46, v0
	v_mov_b32_e32 v47, v0
	v_mov_b32_e32 v52, v0
	v_mov_b32_e32 v53, v0
	v_mov_b32_e32 v54, v0
	v_mov_b32_e32 v55, v0
	v_mov_b32_e32 v60, v0
	v_mov_b32_e32 v61, v0
	v_mov_b32_e32 v62, v0
	v_mov_b32_e32 v63, v0
	v_mov_b32_e32 v64, v0
	v_mov_b32_e32 v65, v0
	v_mov_b32_e32 v66, v0
	v_mov_b32_e32 v67, v0
	v_mov_b32_e32 v72, v0
	v_mov_b32_e32 v73, v0
	v_mov_b32_e32 v74, v0
	v_mov_b32_e32 v75, v0
	v_mov_b32_e32 v80, v0
	v_mov_b32_e32 v81, v0
	v_mov_b32_e32 v82, v0
	v_mov_b32_e32 v83, v0
	v_mov_b32_e32 v88, v0
	v_mov_b32_e32 v89, v0
	v_mov_b32_e32 v90, v0
	v_mov_b32_e32 v91, v0
	v_mov_b32_e32 v96, v0
	v_mov_b32_e32 v97, v0
	v_mov_b32_e32 v98, v0
	v_mov_b32_e32 v99, v0
	v_mov_b32_e32 v104, v0
	v_mov_b32_e32 v105, v0
	v_mov_b32_e32 v106, v0
	v_mov_b32_e32 v107, v0
	v_mov_b32_e32 v112, v0
	v_mov_b32_e32 v113, v0
	v_mov_b32_e32 v114, v0
	v_mov_b32_e32 v115, v0
	v_mov_b32_e32 v120, v0
	v_mov_b32_e32 v121, v0
	v_mov_b32_e32 v122, v0
	v_mov_b32_e32 v123, v0
	v_mov_b32_e32 v68, v0
	v_mov_b32_e32 v69, v0
	v_mov_b32_e32 v70, v0
	v_mov_b32_e32 v71, v0
	v_mov_b32_e32 v76, v0
	v_mov_b32_e32 v77, v0
	v_mov_b32_e32 v78, v0
	v_mov_b32_e32 v79, v0
	v_mov_b32_e32 v84, v0
	v_mov_b32_e32 v85, v0
	v_mov_b32_e32 v86, v0
	v_mov_b32_e32 v87, v0
	v_mov_b32_e32 v92, v0
	v_mov_b32_e32 v93, v0
	v_mov_b32_e32 v94, v0
	v_mov_b32_e32 v95, v0
	v_mov_b32_e32 v100, v0
	v_mov_b32_e32 v101, v0
	v_mov_b32_e32 v102, v0
	v_mov_b32_e32 v103, v0
	v_mov_b32_e32 v108, v0
	v_mov_b32_e32 v109, v0
	v_mov_b32_e32 v110, v0
	v_mov_b32_e32 v111, v0
	v_mov_b32_e32 v116, v0
	v_mov_b32_e32 v117, v0
	v_mov_b32_e32 v118, v0
	v_mov_b32_e32 v119, v0
	v_mov_b32_e32 v124, v0
	v_mov_b32_e32 v125, v0
	v_mov_b32_e32 v126, v0
	v_mov_b32_e32 v127, v0
.LBB0_101:
	s_add_u32 s44, s40, 0xfff80080
	s_addc_u32 s45, s41, -1
	s_cmp_eq_u32 s69, 28
	s_cselect_b32 s47, s5, s45
	s_cselect_b32 s46, s4, s44
	s_cselect_b32 s45, s13, s15
	s_cselect_b32 s44, s12, s9
	s_add_u32 s76, s40, 0xfff80000
	s_addc_u32 s77, s41, -1
	v_add_u32_e32 v140, 0x10000, v205
	ds_read_b128 v[128:131], v140
	ds_read_b128 v[132:135], v140 offset:1024
	ds_read_b128 v[136:139], v140 offset:2048
	ds_read_b128 v[140:143], v140 offset:3072
	v_lshl_add_u64 v[244:245], s[76:77], 0, v[184:185]
	s_add_i32 m0, s92, 0x8000
	v_add_u32_e32 v217, 0x14000, v205
	ds_read_b128 v[188:191], v217
	ds_read_b128 v[196:199], v217 offset:1024
	ds_read_b128 v[200:203], v217 offset:2048
	ds_read_b128 v[218:221], v217 offset:3072
	global_load_lds_dwordx4 v[244:245], off
	v_lshl_add_u64 v[246:247], s[76:77], 0, v[186:187]
	s_add_i32 m0, s92, 0xa000
	ds_read_b128 v[144:147], v216
	ds_read_b128 v[148:151], v216 offset:1024
	ds_read_b128 v[152:155], v216 offset:2048
	ds_read_b128 v[156:159], v216 offset:3072
	global_load_lds_dwordx4 v[246:247], off
	v_lshl_add_u64 v[248:249], s[40:41], 0, v[184:185]
	s_add_i32 m0, s92, 0xc000
	ds_read_b128 v[160:163], v216 offset:4096
	ds_read_b128 v[164:167], v216 offset:5120
	ds_read_b128 v[168:171], v216 offset:6144
	ds_read_b128 v[172:175], v216 offset:7168
	global_load_lds_dwordx4 v[248:249], off
	v_lshl_add_u64 v[250:251], s[40:41], 0, v[186:187]
	s_add_i32 m0, s92, 0xe000
	s_nop 0
	global_load_lds_dwordx4 v[250:251], off
	s_waitcnt lgkmcnt(0)
	s_barrier
; #define PG8_STAGE(bufoff, gbase, voff) do { _Pragma("unroll") for (int _i = 0; _i < 2; ++_i) \
;         __builtin_amdgcn_global_load_lds((const unsigned*)((const char*)(gbase) + (voff)[_i]), (LAS unsigned*)(lds + (bufoff) + ldsw + _i * 8192), 16, 0, 0); } while (0)
; #define PG8_LDA(dst, b, h) do { _Pragma("unroll") for (int m = 0; m < 4; ++m) _Pragma("unroll") for (int k = 0; k < 2; ++k) dst[m][k] = *(const LAS bf16x8*)(lds + PG8_SA(b, h) + aoff + m * 2048 + k * 1024); } while (0)
; #define PG8_LDB(dst, b, h) do { _Pragma("unroll") for (int n = 0; n < 2; ++n) _Pragma("unroll") for (int k = 0; k < 2; ++k) dst[n][k] = *(const LAS bf16x8*)(lds + PG8_SB(b, h) + boff + n * 2048 + k * 1024); } while (0)
; #define PG8_MMA(ai, bj, At, Bt) do { __builtin_amdgcn_s_setprio(1); _Pragma("unroll") for (int m = 0; m < 4; ++m) _Pragma("unroll") for (int n = 0; n < 2; ++n) _Pragma("unroll") for (int k = 0; k < 2; ++k) \
;         acc[ai][bj][m][n] = __builtin_amdgcn_mfma_f32_16x16x32_bf16(Bt[n][k], At[m][k], acc[ai][bj][m][n], 0, 0, 0); __builtin_amdgcn_s_setprio(0); } while (0)
; #define PG8_WAIT_V(n) asm volatile("s_waitcnt vmcnt(" #n ")" ::: "memory")
; #define PG8_WAIT_L(n) asm volatile("s_waitcnt lgkmcnt(" #n ")" ::: "memory")
; #define PG8_BAR __builtin_amdgcn_s_barrier()
; #define PG8_SCHED __builtin_amdgcn_sched_barrier(0)
; template <class Prog>
; __device__ __forceinline__ void gemm_phase(LAS unsigned char* lds, const int K, const Prog& S) {
;     ...
;             PG8_WAIT_L(8); PG8_BAR; PG8_WAIT_L(0); PG8_MMA(0, 0, At, B0); PG8_BAR; PG8_SCHED;
;             PG8_LDB(B1, 0, 1); PG8_STAGE(PG8_SB(0, 0), b2, voffB);
;             PG8_BAR; PG8_WAIT_L(0); PG8_MMA(0, 1, At, B1); PG8_BAR;
;             PG8_LDA(At, 0, 1); PG8_STAGE(PG8_SA(0, 0), a2, voffA);
;             PG8_BAR; PG8_WAIT_L(0); PG8_MMA(1, 0, At, B0); PG8_BAR; PG8_SCHED;
;             PG8_STAGE(PG8_SB(0, 1), b2 + hstep, voffB);
;             PG8_WAIT_V(6); PG8_BAR; PG8_MMA(1, 1, At, B1); PG8_BAR;
	s_setprio 1
	v_mfma_f32_16x16x32_bf16 v[124:127], v[128:131], v[144:147], v[124:127]
	v_mfma_f32_16x16x32_bf16 v[116:119], v[136:139], v[144:147], v[116:119]
	v_mfma_f32_16x16x32_bf16 v[108:111], v[128:131], v[152:155], v[108:111]
	v_mfma_f32_16x16x32_bf16 v[100:103], v[136:139], v[152:155], v[100:103]
	v_mfma_f32_16x16x32_bf16 v[92:95], v[128:131], v[160:163], v[92:95]
	v_mfma_f32_16x16x32_bf16 v[84:87], v[136:139], v[160:163], v[84:87]
	v_mfma_f32_16x16x32_bf16 v[76:79], v[128:131], v[168:171], v[76:79]
	v_mfma_f32_16x16x32_bf16 v[68:71], v[136:139], v[168:171], v[68:71]
	v_mfma_f32_16x16x32_bf16 v[124:127], v[132:135], v[148:151], v[124:127]
	v_mfma_f32_16x16x32_bf16 v[116:119], v[140:143], v[148:151], v[116:119]
	v_mfma_f32_16x16x32_bf16 v[108:111], v[132:135], v[156:159], v[108:111]
	v_mfma_f32_16x16x32_bf16 v[100:103], v[140:143], v[156:159], v[100:103]
	v_mfma_f32_16x16x32_bf16 v[92:95], v[132:135], v[164:167], v[92:95]
	v_mfma_f32_16x16x32_bf16 v[84:87], v[140:143], v[164:167], v[84:87]
	v_mfma_f32_16x16x32_bf16 v[76:79], v[132:135], v[172:175], v[76:79]
	v_mfma_f32_16x16x32_bf16 v[68:71], v[140:143], v[172:175], v[68:71]
	v_mfma_f32_16x16x32_bf16 v[120:123], v[188:191], v[144:147], v[120:123]
	v_mfma_f32_16x16x32_bf16 v[112:115], v[200:203], v[144:147], v[112:115]
	v_mfma_f32_16x16x32_bf16 v[104:107], v[188:191], v[152:155], v[104:107]
	v_mfma_f32_16x16x32_bf16 v[96:99], v[200:203], v[152:155], v[96:99]
	v_mfma_f32_16x16x32_bf16 v[88:91], v[188:191], v[160:163], v[88:91]
	v_mfma_f32_16x16x32_bf16 v[80:83], v[200:203], v[160:163], v[80:83]
	v_mfma_f32_16x16x32_bf16 v[72:75], v[188:191], v[168:171], v[72:75]
	v_mfma_f32_16x16x32_bf16 v[64:67], v[200:203], v[168:171], v[64:67]
	v_mfma_f32_16x16x32_bf16 v[120:123], v[196:199], v[148:151], v[120:123]
	v_mfma_f32_16x16x32_bf16 v[112:115], v[218:221], v[148:151], v[112:115]
	v_mfma_f32_16x16x32_bf16 v[104:107], v[196:199], v[156:159], v[104:107]
	v_mfma_f32_16x16x32_bf16 v[96:99], v[218:221], v[156:159], v[96:99]
	v_mfma_f32_16x16x32_bf16 v[88:91], v[196:199], v[164:167], v[88:91]
	v_mfma_f32_16x16x32_bf16 v[80:83], v[218:221], v[164:167], v[80:83]
	v_mfma_f32_16x16x32_bf16 v[72:75], v[196:199], v[172:175], v[72:75]
	v_mfma_f32_16x16x32_bf16 v[64:67], v[218:221], v[172:175], v[64:67]
	s_setprio 0
	s_barrier
	ds_read_b128 v[144:147], v216 offset:16384
	ds_read_b128 v[148:151], v216 offset:17408
	ds_read_b128 v[152:155], v216 offset:18432
	ds_read_b128 v[156:159], v216 offset:19456
	v_lshl_add_u64 v[244:245], s[44:45], 0, v[192:193]
	s_add_i32 m0, s92, 0x10000
	ds_read_b128 v[160:163], v216 offset:20480
	ds_read_b128 v[164:167], v216 offset:21504
	ds_read_b128 v[168:171], v216 offset:22528
	ds_read_b128 v[172:175], v216 offset:23552
	global_load_lds_dwordx4 v[244:245], off
	v_lshl_add_u64 v[246:247], s[44:45], 0, v[180:181]
	s_add_i32 m0, s92, 0x12000
	s_nop 0
	global_load_lds_dwordx4 v[246:247], off
	s_add_u32 s76, s44, 0x80000
	s_addc_u32 s77, s45, 0
	v_lshl_add_u64 v[248:249], s[76:77], 0, v[192:193]
	s_add_i32 m0, s92, 0x14000
	s_nop 0
	global_load_lds_dwordx4 v[248:249], off
	v_lshl_add_u64 v[250:251], s[76:77], 0, v[180:181]
	s_add_i32 m0, s92, 0x16000
	s_nop 0
	global_load_lds_dwordx4 v[250:251], off
	s_waitcnt vmcnt(4)
	s_waitcnt lgkmcnt(0)
	s_barrier
	s_setprio 1
	v_mfma_f32_16x16x32_bf16 v[60:63], v[128:131], v[144:147], v[60:63]
	v_mfma_f32_16x16x32_bf16 v[52:55], v[136:139], v[144:147], v[52:55]
	v_mfma_f32_16x16x32_bf16 v[44:47], v[128:131], v[152:155], v[44:47]
	v_mfma_f32_16x16x32_bf16 v[36:39], v[136:139], v[152:155], v[36:39]
	v_mfma_f32_16x16x32_bf16 v[28:31], v[128:131], v[160:163], v[28:31]
	v_mfma_f32_16x16x32_bf16 v[20:23], v[136:139], v[160:163], v[20:23]
	v_mfma_f32_16x16x32_bf16 v[12:15], v[128:131], v[168:171], v[12:15]
	v_mfma_f32_16x16x32_bf16 v[4:7], v[136:139], v[168:171], v[4:7]
	v_mfma_f32_16x16x32_bf16 v[60:63], v[132:135], v[148:151], v[60:63]
	v_mfma_f32_16x16x32_bf16 v[52:55], v[140:143], v[148:151], v[52:55]
	v_mfma_f32_16x16x32_bf16 v[44:47], v[132:135], v[156:159], v[44:47]
	v_mfma_f32_16x16x32_bf16 v[36:39], v[140:143], v[156:159], v[36:39]
	v_mfma_f32_16x16x32_bf16 v[28:31], v[132:135], v[164:167], v[28:31]
	v_mfma_f32_16x16x32_bf16 v[20:23], v[140:143], v[164:167], v[20:23]
	v_mfma_f32_16x16x32_bf16 v[12:15], v[132:135], v[172:175], v[12:15]
	v_mfma_f32_16x16x32_bf16 v[4:7], v[140:143], v[172:175], v[4:7]
	v_mfma_f32_16x16x32_bf16 v[56:59], v[188:191], v[144:147], v[56:59]
	v_mfma_f32_16x16x32_bf16 v[48:51], v[200:203], v[144:147], v[48:51]
	v_mfma_f32_16x16x32_bf16 v[40:43], v[188:191], v[152:155], v[40:43]
	v_mfma_f32_16x16x32_bf16 v[32:35], v[200:203], v[152:155], v[32:35]
	v_mfma_f32_16x16x32_bf16 v[24:27], v[188:191], v[160:163], v[24:27]
	v_mfma_f32_16x16x32_bf16 v[16:19], v[200:203], v[160:163], v[16:19]
	v_mfma_f32_16x16x32_bf16 v[8:11], v[188:191], v[168:171], v[8:11]
	v_mfma_f32_16x16x32_bf16 v[0:3], v[200:203], v[168:171], v[0:3]
	v_mfma_f32_16x16x32_bf16 v[56:59], v[196:199], v[148:151], v[56:59]
	v_mfma_f32_16x16x32_bf16 v[48:51], v[218:221], v[148:151], v[48:51]
	v_mfma_f32_16x16x32_bf16 v[40:43], v[196:199], v[156:159], v[40:43]
	v_mfma_f32_16x16x32_bf16 v[32:35], v[218:221], v[156:159], v[32:35]
	v_mfma_f32_16x16x32_bf16 v[24:27], v[196:199], v[164:167], v[24:27]
	v_mfma_f32_16x16x32_bf16 v[16:19], v[218:221], v[164:167], v[16:19]
	v_mfma_f32_16x16x32_bf16 v[8:11], v[196:199], v[172:175], v[8:11]
	v_mfma_f32_16x16x32_bf16 v[0:3], v[218:221], v[172:175], v[0:3]
	s_setprio 0
	s_barrier
; #define PG8_STAGE(bufoff, gbase, voff) do { _Pragma("unroll") for (int _i = 0; _i < 2; ++_i) \
;         __builtin_amdgcn_global_load_lds((const unsigned*)((const char*)(gbase) + (voff)[_i]), (LAS unsigned*)(lds + (bufoff) + ldsw + _i * 8192), 16, 0, 0); } while (0)
; #define PG8_LDA(dst, b, h) do { _Pragma("unroll") for (int m = 0; m < 4; ++m) _Pragma("unroll") for (int k = 0; k < 2; ++k) dst[m][k] = *(const LAS bf16x8*)(lds + PG8_SA(b, h) + aoff + m * 2048 + k * 1024); } while (0)
; #define PG8_LDB(dst, b, h) do { _Pragma("unroll") for (int n = 0; n < 2; ++n) _Pragma("unroll") for (int k = 0; k < 2; ++k) dst[n][k] = *(const LAS bf16x8*)(lds + PG8_SB(b, h) + boff + n * 2048 + k * 1024); } while (0)
; #define PG8_MMA(ai, bj, At, Bt) do { __builtin_amdgcn_s_setprio(1); _Pragma("unroll") for (int m = 0; m < 4; ++m) _Pragma("unroll") for (int n = 0; n < 2; ++n) _Pragma("unroll") for (int k = 0; k < 2; ++k) \
;         acc[ai][bj][m][n] = __builtin_amdgcn_mfma_f32_16x16x32_bf16(Bt[n][k], At[m][k], acc[ai][bj][m][n], 0, 0, 0); __builtin_amdgcn_s_setprio(0); } while (0)
; #define PG8_WAIT_L(n) asm volatile("s_waitcnt lgkmcnt(" #n ")" ::: "memory")
; #define PG8_BAR __builtin_amdgcn_s_barrier()
; #define PG8_SCHED __builtin_amdgcn_sched_barrier(0)
; template <class Prog>
; __device__ __forceinline__ void gemm_phase(LAS unsigned char* lds, const int K, const Prog& S) {
;     ...
;             PG8_LDB(B0, 1, 0); PG8_SCHED; PG8_LDA(At, 1, 0); PG8_STAGE(PG8_SA(0, 1), a2 + hstep, voffA);
;             PG8_WAIT_L(8); PG8_BAR; PG8_WAIT_L(0); PG8_MMA(0, 0, At, B0); PG8_BAR; PG8_SCHED;
;             PG8_LDB(B1, 1, 1); PG8_STAGE(PG8_SB(1, 0), b3, voffB);
;             PG8_BAR; PG8_WAIT_L(0); PG8_MMA(0, 1, At, B1); PG8_BAR;
	s_add_u32 s76, s46, 0x80000
	s_addc_u32 s77, s47, 0
	v_add_u32_e32 v140, 0x18000, v205
	ds_read_b128 v[128:131], v140
	ds_read_b128 v[132:135], v140 offset:1024
	ds_read_b128 v[136:139], v140 offset:2048
	ds_read_b128 v[140:143], v140 offset:3072
	v_lshl_add_u64 v[244:245], s[46:47], 0, v[176:177]
	s_mov_b32 m0, s92
	v_add_u32_e32 v217, 0x1c000, v205
	ds_read_b128 v[188:191], v217
	ds_read_b128 v[196:199], v217 offset:1024
	ds_read_b128 v[200:203], v217 offset:2048
	ds_read_b128 v[218:221], v217 offset:3072
	global_load_lds_dwordx4 v[244:245], off
	v_lshl_add_u64 v[246:247], s[46:47], 0, v[178:179]
	s_add_i32 m0, s92, 0x2000
	ds_read_b128 v[144:147], v216 offset:32768
	ds_read_b128 v[148:151], v216 offset:33792
	ds_read_b128 v[152:155], v216 offset:34816
	ds_read_b128 v[156:159], v216 offset:35840
	global_load_lds_dwordx4 v[246:247], off
	v_lshl_add_u64 v[248:249], s[76:77], 0, v[176:177]
	s_add_i32 m0, s92, 0x4000
	ds_read_b128 v[160:163], v216 offset:36864
	ds_read_b128 v[164:167], v216 offset:37888
	ds_read_b128 v[168:171], v216 offset:38912
	ds_read_b128 v[172:175], v216 offset:39936
	global_load_lds_dwordx4 v[248:249], off
	v_lshl_add_u64 v[250:251], s[76:77], 0, v[178:179]
	s_add_i32 m0, s92, 0x6000
	s_nop 0
	global_load_lds_dwordx4 v[250:251], off
	s_waitcnt lgkmcnt(0)
	s_barrier
	s_setprio 1
	v_mfma_f32_16x16x32_bf16 v[124:127], v[128:131], v[144:147], v[124:127]
	v_mfma_f32_16x16x32_bf16 v[116:119], v[136:139], v[144:147], v[116:119]
	v_mfma_f32_16x16x32_bf16 v[108:111], v[128:131], v[152:155], v[108:111]
	v_mfma_f32_16x16x32_bf16 v[100:103], v[136:139], v[152:155], v[100:103]
	v_mfma_f32_16x16x32_bf16 v[92:95], v[128:131], v[160:163], v[92:95]
	v_mfma_f32_16x16x32_bf16 v[84:87], v[136:139], v[160:163], v[84:87]
	v_mfma_f32_16x16x32_bf16 v[76:79], v[128:131], v[168:171], v[76:79]
	v_mfma_f32_16x16x32_bf16 v[68:71], v[136:139], v[168:171], v[68:71]
	v_mfma_f32_16x16x32_bf16 v[124:127], v[132:135], v[148:151], v[124:127]
	v_mfma_f32_16x16x32_bf16 v[116:119], v[140:143], v[148:151], v[116:119]
	v_mfma_f32_16x16x32_bf16 v[108:111], v[132:135], v[156:159], v[108:111]
	v_mfma_f32_16x16x32_bf16 v[100:103], v[140:143], v[156:159], v[100:103]
	v_mfma_f32_16x16x32_bf16 v[92:95], v[132:135], v[164:167], v[92:95]
	v_mfma_f32_16x16x32_bf16 v[84:87], v[140:143], v[164:167], v[84:87]
	v_mfma_f32_16x16x32_bf16 v[76:79], v[132:135], v[172:175], v[76:79]
	v_mfma_f32_16x16x32_bf16 v[68:71], v[140:143], v[172:175], v[68:71]
	v_mfma_f32_16x16x32_bf16 v[120:123], v[188:191], v[144:147], v[120:123]
	v_mfma_f32_16x16x32_bf16 v[112:115], v[200:203], v[144:147], v[112:115]
	v_mfma_f32_16x16x32_bf16 v[104:107], v[188:191], v[152:155], v[104:107]
	v_mfma_f32_16x16x32_bf16 v[96:99], v[200:203], v[152:155], v[96:99]
	v_mfma_f32_16x16x32_bf16 v[88:91], v[188:191], v[160:163], v[88:91]
	v_mfma_f32_16x16x32_bf16 v[80:83], v[200:203], v[160:163], v[80:83]
	v_mfma_f32_16x16x32_bf16 v[72:75], v[188:191], v[168:171], v[72:75]
	v_mfma_f32_16x16x32_bf16 v[64:67], v[200:203], v[168:171], v[64:67]
	v_mfma_f32_16x16x32_bf16 v[120:123], v[196:199], v[148:151], v[120:123]
	v_mfma_f32_16x16x32_bf16 v[112:115], v[218:221], v[148:151], v[112:115]
	v_mfma_f32_16x16x32_bf16 v[104:107], v[196:199], v[156:159], v[104:107]
	v_mfma_f32_16x16x32_bf16 v[96:99], v[218:221], v[156:159], v[96:99]
	v_mfma_f32_16x16x32_bf16 v[88:91], v[196:199], v[164:167], v[88:91]
	v_mfma_f32_16x16x32_bf16 v[80:83], v[218:221], v[164:167], v[80:83]
	v_mfma_f32_16x16x32_bf16 v[72:75], v[196:199], v[172:175], v[72:75]
	v_mfma_f32_16x16x32_bf16 v[64:67], v[218:221], v[172:175], v[64:67]
	s_setprio 0
	s_barrier
; #define PG8_STAGE(bufoff, gbase, voff) do { _Pragma("unroll") for (int _i = 0; _i < 2; ++_i) \
;         __builtin_amdgcn_global_load_lds((const unsigned*)((const char*)(gbase) + (voff)[_i]), (LAS unsigned*)(lds + (bufoff) + ldsw + _i * 8192), 16, 0, 0); } while (0)
; #define PG8_LDA(dst, b, h) do { _Pragma("unroll") for (int m = 0; m < 4; ++m) _Pragma("unroll") for (int k = 0; k < 2; ++k) dst[m][k] = *(const LAS bf16x8*)(lds + PG8_SA(b, h) + aoff + m * 2048 + k * 1024); } while (0)
; #define PG8_MMA(ai, bj, At, Bt) do { __builtin_amdgcn_s_setprio(1); _Pragma("unroll") for (int m = 0; m < 4; ++m) _Pragma("unroll") for (int n = 0; n < 2; ++n) _Pragma("unroll") for (int k = 0; k < 2; ++k) \
;         acc[ai][bj][m][n] = __builtin_amdgcn_mfma_f32_16x16x32_bf16(Bt[n][k], At[m][k], acc[ai][bj][m][n], 0, 0, 0); __builtin_amdgcn_s_setprio(0); } while (0)
; #define PG8_WAIT_V(n) asm volatile("s_waitcnt vmcnt(" #n ")" ::: "memory")
; #define PG8_WAIT_L(n) asm volatile("s_waitcnt lgkmcnt(" #n ")" ::: "memory")
; #define PG8_BAR __builtin_amdgcn_s_barrier()
; #define PG8_SCHED __builtin_amdgcn_sched_barrier(0)
; template <class Prog>
; __device__ __forceinline__ void gemm_phase(LAS unsigned char* lds, const int K, const Prog& S) {
;     ...
;             PG8_LDA(At, 1, 1); PG8_STAGE(PG8_SA(1, 0), a3, voffA);
;             PG8_BAR; PG8_WAIT_L(0); PG8_MMA(1, 0, At, B0); PG8_BAR; PG8_SCHED;
;             PG8_STAGE(PG8_SB(1, 1), b3 + hstep, voffB);
;             PG8_WAIT_V(6); PG8_BAR; PG8_MMA(1, 1, At, B1); PG8_BAR;
;         }
;         S.epi(acc, cur, wr, wc, fr, fq);
;     __device__ __forceinline__ void epi(f32x4 (&acc)[2][2][4][2], const pg8::Unit& u, int wr, int wc, int fr, int fq) const {
;     ...
;         const int mode = (pn < 8) ? 1 : ((pn >= 12 && pn < 16) || (pn >= 20 && pn < 24) || (pn >= 30 && pn < 34)) ? 2 : (pn >= 34 ? 3 : 0);
	s_add_u32 s76, s44, 0x80
	s_addc_u32 s77, s45, 0
	ds_read_b128 v[144:147], v216 offset:49152
	ds_read_b128 v[148:151], v216 offset:50176
	ds_read_b128 v[152:155], v216 offset:51200
	ds_read_b128 v[156:159], v216 offset:52224
	v_lshl_add_u64 v[244:245], s[76:77], 0, v[192:193]
	s_add_i32 m0, s92, 0x18000
	ds_read_b128 v[160:163], v216 offset:53248
	ds_read_b128 v[164:167], v216 offset:54272
	ds_read_b128 v[168:171], v216 offset:55296
	ds_read_b128 v[172:175], v216 offset:56320
	global_load_lds_dwordx4 v[244:245], off
	v_lshl_add_u64 v[246:247], s[76:77], 0, v[180:181]
	s_add_i32 m0, s92, 0x1a000
	s_nop 0
	global_load_lds_dwordx4 v[246:247], off
	s_add_u32 s76, s44, 0x80080
	s_addc_u32 s77, s45, 0
	v_lshl_add_u64 v[248:249], s[76:77], 0, v[192:193]
	s_add_i32 m0, s92, 0x1c000
	s_nop 0
	global_load_lds_dwordx4 v[248:249], off
	v_lshl_add_u64 v[250:251], s[76:77], 0, v[180:181]
	s_add_i32 m0, s92, 0x1e000
	s_nop 0
	global_load_lds_dwordx4 v[250:251], off
	s_waitcnt vmcnt(4)
	s_waitcnt lgkmcnt(0)
	s_barrier
	s_setprio 1
	v_mfma_f32_16x16x32_bf16 v[60:63], v[128:131], v[144:147], v[60:63]
	v_mfma_f32_16x16x32_bf16 v[52:55], v[136:139], v[144:147], v[52:55]
	v_mfma_f32_16x16x32_bf16 v[44:47], v[128:131], v[152:155], v[44:47]
	v_mfma_f32_16x16x32_bf16 v[36:39], v[136:139], v[152:155], v[36:39]
	v_mfma_f32_16x16x32_bf16 v[28:31], v[128:131], v[160:163], v[28:31]
	v_mfma_f32_16x16x32_bf16 v[20:23], v[136:139], v[160:163], v[20:23]
	v_mfma_f32_16x16x32_bf16 v[12:15], v[128:131], v[168:171], v[12:15]
	v_mfma_f32_16x16x32_bf16 v[4:7], v[136:139], v[168:171], v[4:7]
	v_mfma_f32_16x16x32_bf16 v[60:63], v[132:135], v[148:151], v[60:63]
	v_mfma_f32_16x16x32_bf16 v[52:55], v[140:143], v[148:151], v[52:55]
	v_mfma_f32_16x16x32_bf16 v[44:47], v[132:135], v[156:159], v[44:47]
	v_mfma_f32_16x16x32_bf16 v[36:39], v[140:143], v[156:159], v[36:39]
	v_mfma_f32_16x16x32_bf16 v[28:31], v[132:135], v[164:167], v[28:31]
	v_mfma_f32_16x16x32_bf16 v[20:23], v[140:143], v[164:167], v[20:23]
	v_mfma_f32_16x16x32_bf16 v[12:15], v[132:135], v[172:175], v[12:15]
	v_mfma_f32_16x16x32_bf16 v[4:7], v[140:143], v[172:175], v[4:7]
	v_mfma_f32_16x16x32_bf16 v[56:59], v[188:191], v[144:147], v[56:59]
	v_mfma_f32_16x16x32_bf16 v[48:51], v[200:203], v[144:147], v[48:51]
	v_mfma_f32_16x16x32_bf16 v[40:43], v[188:191], v[152:155], v[40:43]
	v_mfma_f32_16x16x32_bf16 v[32:35], v[200:203], v[152:155], v[32:35]
	v_mfma_f32_16x16x32_bf16 v[24:27], v[188:191], v[160:163], v[24:27]
	v_mfma_f32_16x16x32_bf16 v[16:19], v[200:203], v[160:163], v[16:19]
	v_mfma_f32_16x16x32_bf16 v[8:11], v[188:191], v[168:171], v[8:11]
	v_mfma_f32_16x16x32_bf16 v[0:3], v[200:203], v[168:171], v[0:3]
	v_mfma_f32_16x16x32_bf16 v[56:59], v[196:199], v[148:151], v[56:59]
	v_mfma_f32_16x16x32_bf16 v[48:51], v[218:221], v[148:151], v[48:51]
	v_mfma_f32_16x16x32_bf16 v[40:43], v[196:199], v[156:159], v[40:43]
	v_mfma_f32_16x16x32_bf16 v[32:35], v[218:221], v[156:159], v[32:35]
	v_mfma_f32_16x16x32_bf16 v[24:27], v[196:199], v[164:167], v[24:27]
	v_mfma_f32_16x16x32_bf16 v[16:19], v[218:221], v[164:167], v[16:19]
	v_mfma_f32_16x16x32_bf16 v[8:11], v[196:199], v[172:175], v[8:11]
	v_mfma_f32_16x16x32_bf16 v[0:3], v[218:221], v[172:175], v[0:3]
	s_setprio 0
	s_add_i32 s69, s69, 2
	s_add_u32 s40, s40, 0x100
	s_addc_u32 s41, s41, 0
	s_add_u32 s9, s9, 0x100
	s_addc_u32 s15, s15, 0
	s_cmp_gt_u32 s69, 29
	s_barrier
	s_cbranch_scc0 .LBB0_101
	s_cmp_lt_i32 s75, 8
	s_mov_b32 s9, 1
	s_cbranch_scc1 .LBB0_110
	s_sub_i32 s4, s75, 30
	s_cmp_lt_u32 s4, 4
	s_mov_b32 s9, 2
	s_cbranch_scc1 .LBB0_110
	s_and_b32 s9, s75, 0x7ffffffc
	s_cmp_lt_i32 s9, 20
	s_cbranch_scc1 .LBB0_106
	s_cmp_lg_u32 s9, 20
	s_cselect_b64 s[4:5], -1, 0
	s_cbranch_execz .LBB0_107
	s_branch .LBB0_108

; #define LAS __attribute__((address_space(3)))
; __device__ __forceinline__ void scan_item(const Args& a, int l, int it, LAS unsigned char* lds, int tid) {
;     const bf16_t* Z = (const bf16_t*)(a.ws + WS_Z);
;     const int lane = tid & 63, wave = tid >> 6, fr = lane & 15, fq = lane >> 4;
;     const int dsl = it & 3, dir = (it >> 2) & 1, bh = it >> 3, b = bh >> 2, h = bh & 3;
;     bf16_t* ST = (bf16_t*)(a.ws + (dir ? WS_SB : WS_SF)) + (size_t)bh * 32 * 65536;
;     const float lg = -expf(a.in[dir ? 4 : 3][l * 4 + h]); const float dec = expf(lg * 128.f);
;     LAS unsigned char* Ks = lds; LAS unsigned char* Vs = lds + 20480;
;     f32x4 st[4][2];
; #pragma unroll
;     for (int dt = 0; dt < 4; ++dt) { st[dt][0] = (f32x4){0.f, 0.f, 0.f, 0.f}; st[dt][1] = (f32x4){0.f, 0.f, 0.f, 0.f}; }
;     u32x4 vrA[8], krA[2], vrB[8], krB[2];
;     const bf16_t* zb = Z + (size_t)(b * SEQ) * NIN + h * 256;
.LBB0_217:
	s_andn2_b64 vcc, exec, s[2:3]
	s_cbranch_vccnz .LBB0_314
	s_waitcnt lgkmcnt(0)
	v_mov_b32_e32 v1, v222
	s_lshl_b32 s8, s69, 2
	s_mov_b32 s9, s81
	s_lshl_b64 s[2:3], s[8:9], 2
	v_add_u32_e32 v4, 0x200, v1
	v_add_u32_e32 v6, 0x400, v1
	v_add_u32_e32 v7, 0x600, v1
	v_add_u32_e32 v8, 0x800, v1
	v_add_u32_e32 v9, 0xa00, v1
	v_add_u32_e32 v10, 0xc00, v1
	v_add_u32_e32 v11, 0xe00, v1
	v_readlane_b32 s4, v254, 34
	v_ashrrev_i32_e32 v3, 5, v1
	v_ashrrev_i32_e32 v5, 5, v4
	v_ashrrev_i32_e32 v6, 5, v6
	v_ashrrev_i32_e32 v7, 5, v7
	v_ashrrev_i32_e32 v8, 5, v8
	v_ashrrev_i32_e32 v9, 5, v9
	v_ashrrev_i32_e32 v10, 5, v10
	v_ashrrev_i32_e32 v11, 5, v11
	v_ashrrev_i32_e32 v12, 3, v1
	v_ashrrev_i32_e32 v4, 3, v4
	s_add_u32 s6, s4, s2
	v_mad_i64_i32 v[114:115], s[4:5], v3, s58, 0
	v_mad_i64_i32 v[116:117], s[4:5], v5, s58, 0
	v_mad_i64_i32 v[118:119], s[4:5], v6, s58, 0
	v_mad_i64_i32 v[120:121], s[4:5], v7, s58, 0
	v_mad_i64_i32 v[122:123], s[4:5], v8, s58, 0
	v_mad_i64_i32 v[124:125], s[4:5], v9, s58, 0
	v_mad_i64_i32 v[126:127], s[4:5], v10, s58, 0
	v_mad_i64_i32 v[128:129], s[4:5], v11, s58, 0
	v_mad_i64_i32 v[132:133], s[4:5], v12, s58, 0
	s_waitcnt lgkmcnt(0)
	v_mad_i64_i32 v[134:135], s[4:5], v4, s58, 0
	v_and_b32_e32 v0, 15, v1
	v_lshlrev_b32_e32 v2, 3, v1
	v_ashrrev_i32_e32 v15, 1, v1
	s_movk_i32 s4, 0xffe0
	v_readlane_b32 s2, v254, 35
	v_and_b32_e32 v112, 0xf8, v2
	v_and_b32_e32 v130, 56, v2
	v_and_or_b32 v0, v15, s4, v0
	v_lshrrev_b32_e32 v15, 2, v1
	v_and_b32_e32 v2, 24, v2
	s_addc_u32 s7, s2, s3
	v_cmp_eq_u32_e64 s[2:3], 0, v1
	v_lshlrev_b32_e32 v13, 4, v1
	v_and_b32_e32 v113, 12, v15
	v_bfe_u32 v15, v1, 2, 4
	v_add_u32_e32 v2, 0, v2
	v_and_b32_e32 v1, 0xffffffc0, v1
	v_add_u32_e32 v16, v2, v1
	v_sub_u32_e32 v1, 0x7f, v12
	v_cvt_f32_i32_e32 v152, v1
	v_sub_u32_e32 v1, 0x7f, v4
	v_cvt_f32_i32_e32 v154, v1
	v_ashrrev_i32_e32 v1, 31, v0
	v_cvt_f32_i32_e32 v131, v12
	v_cvt_f32_i32_e32 v153, v4
	v_lshlrev_b64 v[136:137], 9, v[0:1]
	v_or_b32_e32 v0, 16, v0
	v_and_b32_e32 v14, 0x1f0, v13
	v_and_b32_e32 v13, 0x70, v13
	s_movk_i32 s4, 0xa0
	v_ashrrev_i32_e32 v1, 31, v0
	v_mov_b32_e32 v17, 0x4400
	v_add_u32_e32 v14, 0, v14
	v_add_u32_e32 v13, 0, v13
	v_mul_lo_u32 v3, v3, s59
	v_mul_lo_u32 v5, v5, s59
	v_mul_lo_u32 v6, v6, s59
	v_mul_lo_u32 v7, v7, s59
	v_mul_lo_u32 v8, v8, s59
	v_mul_lo_u32 v9, v9, s59
	v_mul_lo_u32 v10, v10, s59
	v_mul_lo_u32 v11, v11, s59
	v_mul_lo_u32 v12, v12, s4
	v_mul_lo_u32 v4, v4, s4
	v_lshlrev_b64 v[138:139], 9, v[0:1]
	v_bfe_u32 v196, v222, 4, 1
	v_mul_u32_u24_e32 v196, 24, v196
	v_add_u32_e32 v136, v136, v196
	v_add_u32_e32 v138, v138, v196
	v_mul_u32_u24_e32 v0, 0xa0, v15
	v_mul_u32_u24_e32 v1, 0x220, v15
	v_mad_u32_u24 v15, v15, s59, v17
	v_add_u32_e32 v155, v14, v3
	v_add_u32_e32 v156, v14, v5
	v_add_u32_e32 v157, v14, v6
	v_add_u32_e32 v158, v14, v7
	v_add_u32_e32 v159, v14, v8
	v_add_u32_e32 v160, v14, v9
	v_add_u32_e32 v161, v14, v10
	v_add_u32_e32 v162, v14, v11
	v_add_u32_e32 v163, v13, v12
	v_add_u32_e32 v164, v13, v4
	v_add_u32_e32 v165, v2, v0
	v_add_u32_e32 v166, v16, v1
	v_add_u32_e32 v167, v16, v15
	s_branch .LBB0_221

.LBB0_227:
	s_add_i32 s41, s40, -2
	s_add_i32 s44, s12, 2
	s_and_b64 s[42:43], s[4:5], exec
	s_cselect_b32 s41, s41, s44
	s_lshl_b32 s80, s41, 17
	v_lshl_add_u64 v[148:149], v[146:147], 0, s[80:81]
	v_lshl_add_u64 v[170:171], v[148:149], 0, v[136:137]
	v_lshl_add_u64 v[148:149], v[148:149], 0, v[138:139]
	v_cvt_pk_bf16_f32 v196, v108, v109
	v_cvt_pk_bf16_f32 v197, v110, v111
	v_cvt_pk_bf16_f32 v198, v100, v101
	v_cvt_pk_bf16_f32 v199, v102, v103
	v_cvt_pk_bf16_f32 v200, v104, v105
	v_cvt_pk_bf16_f32 v201, v106, v107
	v_cvt_pk_bf16_f32 v202, v96, v97
	v_cvt_pk_bf16_f32 v203, v98, v99
	s_nop 1
	v_permlane16_swap_b32_e32 v196, v198
	v_permlane16_swap_b32_e32 v197, v199
	v_permlane16_swap_b32_e32 v200, v202
	v_permlane16_swap_b32_e32 v201, v203
	global_store_dwordx4 v[170:171], v[196:199], off
	global_store_dwordx4 v[148:149], v[200:203], off
	s_nop 1
	v_cvt_pk_bf16_f32 v196, v92, v93
	v_cvt_pk_bf16_f32 v197, v94, v95
	v_cvt_pk_bf16_f32 v198, v88, v89
	v_cvt_pk_bf16_f32 v199, v90, v91
	v_cvt_pk_bf16_f32 v200, v80, v81
	v_cvt_pk_bf16_f32 v201, v82, v83
	v_cvt_pk_bf16_f32 v202, v84, v85
	v_cvt_pk_bf16_f32 v203, v86, v87
	s_nop 1
	v_permlane16_swap_b32_e32 v196, v198
	v_permlane16_swap_b32_e32 v197, v199
	v_permlane16_swap_b32_e32 v200, v202
	v_permlane16_swap_b32_e32 v201, v203
	global_store_dwordx4 v[170:171], v[196:199], off offset:64
	global_store_dwordx4 v[148:149], v[200:203], off offset:64
	ds_read_b64_tr_b16 v[172:173], v165 offset:2560
	ds_read_b64_tr_b16 v[170:171], v165
	ds_read_b64_tr_b16 v[176:177], v166 offset:29184
	ds_read_b64_tr_b16 v[174:175], v166 offset:20480
	ds_read_b64_tr_b16 v[178:179], v165 offset:32
	ds_read_b64_tr_b16 v[180:181], v165 offset:2592
	ds_read_b64_tr_b16 v[182:183], v166 offset:20512
	ds_read_b64_tr_b16 v[184:185], v166 offset:29216
	v_pk_mul_f32 v[110:111], v[142:143], v[110:111]
	v_pk_mul_f32 v[108:109], v[144:145], v[108:109]
	v_pk_mul_f32 v[106:107], v[142:143], v[106:107]
	v_pk_mul_f32 v[104:105], v[144:145], v[104:105]
	v_pk_mul_f32 v[102:103], v[142:143], v[102:103]
	v_pk_mul_f32 v[100:101], v[144:145], v[100:101]
	v_pk_mul_f32 v[98:99], v[142:143], v[98:99]
	v_pk_mul_f32 v[96:97], v[144:145], v[96:97]
	s_waitcnt lgkmcnt(4)
	v_mfma_f32_16x16x32_bf16 v[108:111], v[170:173], v[174:177], v[108:111]
	v_mul_f32_e64 v94, v142, v94
	v_mul_f32_e64 v95, v143, v95
	v_pk_mul_f32 v[92:93], v[144:145], v[92:93]
	v_pk_mul_f32 v[82:83], v[142:143], v[82:83]
	s_waitcnt lgkmcnt(0)
	v_mfma_f32_16x16x32_bf16 v[104:107], v[170:173], v[182:185], v[104:107]
	ds_read_b64_tr_b16 v[170:171], v165 offset:64
	ds_read_b64_tr_b16 v[172:173], v165 offset:2624
	v_pk_mul_f32 v[80:81], v[144:145], v[80:81]
	v_mfma_f32_16x16x32_bf16 v[100:103], v[178:181], v[174:177], v[100:103]
	v_mul_f32_e64 v90, v142, v90
	v_mul_f32_e64 v91, v143, v91
	v_pk_mul_f32 v[88:89], v[144:145], v[88:89]
	v_pk_mul_f32 v[86:87], v[142:143], v[86:87]
	v_mfma_f32_16x16x32_bf16 v[96:99], v[178:181], v[182:185], v[96:99]
	ds_read_b64_tr_b16 v[180:181], v165 offset:2656
	ds_read_b64_tr_b16 v[178:179], v165 offset:96
	v_pk_mul_f32 v[84:85], v[144:145], v[84:85]
	s_waitcnt lgkmcnt(2)
	v_mfma_f32_16x16x32_bf16 v[92:95], v[170:173], v[174:177], v[92:95]
	s_add_i32 s40, s40, 2
	s_add_i32 s12, s12, -2
	s_cmp_gt_u32 s13, 29
	v_mfma_f32_16x16x32_bf16 v[80:83], v[170:173], v[182:185], v[80:83]
	ds_read_b64_tr_b16 v[170:171], v165 offset:5120
	ds_read_b64_tr_b16 v[172:173], v165 offset:7680
	s_waitcnt lgkmcnt(2)
	v_mfma_f32_16x16x32_bf16 v[88:91], v[178:181], v[174:177], v[88:91]
	v_mfma_f32_16x16x32_bf16 v[84:87], v[178:181], v[182:185], v[84:87]
	ds_read_b64_tr_b16 v[174:175], v166 offset:37888
	ds_read_b64_tr_b16 v[176:177], v166 offset:46592
	ds_read_b64_tr_b16 v[178:179], v166 offset:37920
	ds_read_b64_tr_b16 v[180:181], v166 offset:46624
	ds_read_b64_tr_b16 v[182:183], v165 offset:5152
	ds_read_b64_tr_b16 v[184:185], v165 offset:7712
	s_waitcnt lgkmcnt(4)
	v_mfma_f32_16x16x32_bf16 v[108:111], v[170:173], v[174:177], v[108:111]
	s_waitcnt lgkmcnt(2)
	v_mfma_f32_16x16x32_bf16 v[104:107], v[170:173], v[178:181], v[104:107]
	ds_read_b64_tr_b16 v[170:171], v165 offset:5184
	ds_read_b64_tr_b16 v[172:173], v165 offset:7744
	s_waitcnt lgkmcnt(2)
	v_mfma_f32_16x16x32_bf16 v[100:103], v[182:185], v[174:177], v[100:103]
	v_mfma_f32_16x16x32_bf16 v[96:99], v[182:185], v[178:181], v[96:99]
	ds_read_b64_tr_b16 v[184:185], v165 offset:7776
	ds_read_b64_tr_b16 v[182:183], v165 offset:5216
	s_waitcnt lgkmcnt(2)
	v_mfma_f32_16x16x32_bf16 v[92:95], v[170:173], v[174:177], v[92:95]
	v_mfma_f32_16x16x32_bf16 v[80:83], v[170:173], v[178:181], v[80:83]
	ds_read_b64_tr_b16 v[170:171], v165 offset:10240
	ds_read_b64_tr_b16 v[172:173], v165 offset:12800
	s_waitcnt lgkmcnt(2)
	v_mfma_f32_16x16x32_bf16 v[88:91], v[182:185], v[174:177], v[88:91]
	v_mfma_f32_16x16x32_bf16 v[84:87], v[182:185], v[178:181], v[84:87]
	ds_read_b64_tr_b16 v[174:175], v166 offset:55296
	ds_read_b64_tr_b16 v[176:177], v166 offset:64000
	ds_read_b64_tr_b16 v[178:179], v166 offset:55328
	ds_read_b64_tr_b16 v[180:181], v166 offset:64032
	ds_read_b64_tr_b16 v[182:183], v165 offset:10272
	ds_read_b64_tr_b16 v[184:185], v165 offset:12832
	s_waitcnt lgkmcnt(4)
	v_mfma_f32_16x16x32_bf16 v[108:111], v[170:173], v[174:177], v[108:111]
	s_waitcnt lgkmcnt(2)
	v_mfma_f32_16x16x32_bf16 v[104:107], v[170:173], v[178:181], v[104:107]
	ds_read_b64_tr_b16 v[170:171], v165 offset:10304
	ds_read_b64_tr_b16 v[172:173], v165 offset:12864
	s_waitcnt lgkmcnt(2)
	v_mfma_f32_16x16x32_bf16 v[100:103], v[182:185], v[174:177], v[100:103]
	v_mfma_f32_16x16x32_bf16 v[96:99], v[182:185], v[178:181], v[96:99]
	ds_read_b64_tr_b16 v[184:185], v165 offset:12896
	ds_read_b64_tr_b16 v[182:183], v165 offset:10336
	s_waitcnt lgkmcnt(2)
	v_mfma_f32_16x16x32_bf16 v[92:95], v[170:173], v[174:177], v[92:95]
	v_mfma_f32_16x16x32_bf16 v[80:83], v[170:173], v[178:181], v[80:83]
	ds_read_b64_tr_b16 v[170:171], v165 offset:15360
	ds_read_b64_tr_b16 v[172:173], v165 offset:17920
	s_waitcnt lgkmcnt(2)
	v_mfma_f32_16x16x32_bf16 v[88:91], v[182:185], v[174:177], v[88:91]
	v_mfma_f32_16x16x32_bf16 v[174:177], v[182:185], v[178:181], v[84:87]
	ds_read_b64_tr_b16 v[180:181], v167 offset:64000
	ds_read_b64_tr_b16 v[178:179], v167 offset:55296
	ds_read_b64_tr_b16 v[182:183], v167 offset:55328
	ds_read_b64_tr_b16 v[184:185], v167 offset:64032
	ds_read_b64_tr_b16 v[84:85], v165 offset:15392
	ds_read_b64_tr_b16 v[86:87], v165 offset:17952
	s_waitcnt lgkmcnt(4)
	v_mfma_f32_16x16x32_bf16 v[108:111], v[170:173], v[178:181], v[108:111]
	ds_read_b64_tr_b16 v[188:189], v165 offset:18016
	s_waitcnt lgkmcnt(3)
	v_mfma_f32_16x16x32_bf16 v[104:107], v[170:173], v[182:185], v[104:107]
	ds_read_b64_tr_b16 v[170:171], v165 offset:15424
	ds_read_b64_tr_b16 v[172:173], v165 offset:17984
	ds_read_b64_tr_b16 v[186:187], v165 offset:15456
	s_waitcnt lgkmcnt(4)
	v_mfma_f32_16x16x32_bf16 v[100:103], v[84:87], v[178:181], v[100:103]
	s_waitcnt lgkmcnt(0)
	s_barrier
	v_mfma_f32_16x16x32_bf16 v[96:99], v[84:87], v[182:185], v[96:99]
	v_mfma_f32_16x16x32_bf16 v[92:95], v[170:173], v[178:181], v[92:95]
	v_mfma_f32_16x16x32_bf16 v[84:87], v[170:173], v[182:185], v[80:83]
	v_mfma_f32_16x16x32_bf16 v[88:91], v[186:189], v[178:181], v[88:91]
	v_mfma_f32_16x16x32_bf16 v[80:83], v[186:189], v[182:185], v[174:177]
	s_cbranch_scc1 .LBB0_219

.LBB0_230:
	s_add_i32 s41, s12, 3
	s_and_b64 s[42:43], s[4:5], exec
	s_cselect_b32 s41, s13, s41
	s_lshl_b32 s80, s41, 17
	v_lshl_add_u64 v[148:149], v[146:147], 0, s[80:81]
	v_lshl_add_u64 v[170:171], v[148:149], 0, v[136:137]
	v_lshl_add_u64 v[148:149], v[148:149], 0, v[138:139]
	v_cvt_pk_bf16_f32 v196, v108, v109
	v_cvt_pk_bf16_f32 v197, v110, v111
	v_cvt_pk_bf16_f32 v198, v100, v101
	v_cvt_pk_bf16_f32 v199, v102, v103
	v_cvt_pk_bf16_f32 v200, v104, v105
	v_cvt_pk_bf16_f32 v201, v106, v107
	v_cvt_pk_bf16_f32 v202, v96, v97
	v_cvt_pk_bf16_f32 v203, v98, v99
	s_nop 1
	v_permlane16_swap_b32_e32 v196, v198
	v_permlane16_swap_b32_e32 v197, v199
	v_permlane16_swap_b32_e32 v200, v202
	v_permlane16_swap_b32_e32 v201, v203
	global_store_dwordx4 v[170:171], v[196:199], off
	global_store_dwordx4 v[148:149], v[200:203], off
	s_nop 1
	v_cvt_pk_bf16_f32 v196, v92, v93
	v_cvt_pk_bf16_f32 v197, v94, v95
	v_cvt_pk_bf16_f32 v198, v88, v89
	v_cvt_pk_bf16_f32 v199, v90, v91
	v_cvt_pk_bf16_f32 v200, v84, v85
	v_cvt_pk_bf16_f32 v201, v86, v87
	v_cvt_pk_bf16_f32 v202, v80, v81
	v_cvt_pk_bf16_f32 v203, v82, v83
	s_nop 1
	v_permlane16_swap_b32_e32 v196, v198
	v_permlane16_swap_b32_e32 v197, v199
	v_permlane16_swap_b32_e32 v200, v202
	v_permlane16_swap_b32_e32 v201, v203
	global_store_dwordx4 v[170:171], v[196:199], off offset:64
	global_store_dwordx4 v[148:149], v[200:203], off offset:64
	ds_read_b64_tr_b16 v[172:173], v165 offset:2560
	ds_read_b64_tr_b16 v[170:171], v165
	ds_read_b64_tr_b16 v[176:177], v166 offset:29184
	ds_read_b64_tr_b16 v[174:175], v166 offset:20480
	ds_read_b64_tr_b16 v[178:179], v165 offset:32
	ds_read_b64_tr_b16 v[180:181], v165 offset:2592
	ds_read_b64_tr_b16 v[182:183], v166 offset:20512
	ds_read_b64_tr_b16 v[184:185], v166 offset:29216
	v_mov_b32_e32 v143, v142
	v_pk_mul_f32 v[110:111], v[142:143], v[110:111]
	v_pk_mul_f32 v[108:109], v[144:145], v[108:109]
	v_pk_mul_f32 v[106:107], v[142:143], v[106:107]
	v_pk_mul_f32 v[104:105], v[144:145], v[104:105]
	v_pk_mul_f32 v[102:103], v[142:143], v[102:103]
	v_pk_mul_f32 v[100:101], v[144:145], v[100:101]
	v_pk_mul_f32 v[98:99], v[142:143], v[98:99]
	v_pk_mul_f32 v[96:97], v[144:145], v[96:97]
	s_waitcnt lgkmcnt(4)
	v_mfma_f32_16x16x32_bf16 v[108:111], v[170:173], v[174:177], v[108:111]
	v_mul_f32_e64 v94, v142, v94
	v_mul_f32_e64 v95, v143, v95
	v_pk_mul_f32 v[92:93], v[144:145], v[92:93]
	v_pk_mul_f32 v[86:87], v[142:143], v[86:87]
	s_waitcnt lgkmcnt(0)
	v_mfma_f32_16x16x32_bf16 v[104:107], v[170:173], v[182:185], v[104:107]
	ds_read_b64_tr_b16 v[170:171], v165 offset:64
	ds_read_b64_tr_b16 v[172:173], v165 offset:2624
	v_pk_mul_f32 v[84:85], v[144:145], v[84:85]
	v_mfma_f32_16x16x32_bf16 v[100:103], v[178:181], v[174:177], v[100:103]
	v_mul_f32_e64 v90, v142, v90
	v_mul_f32_e64 v91, v143, v91
	v_pk_mul_f32 v[88:89], v[144:145], v[88:89]
	v_pk_mul_f32 v[82:83], v[142:143], v[82:83]
	v_mfma_f32_16x16x32_bf16 v[96:99], v[178:181], v[182:185], v[96:99]
	ds_read_b64_tr_b16 v[180:181], v165 offset:2656
	ds_read_b64_tr_b16 v[178:179], v165 offset:96
	v_pk_mul_f32 v[80:81], v[144:145], v[80:81]
	s_waitcnt lgkmcnt(2)
	v_mfma_f32_16x16x32_bf16 v[92:95], v[170:173], v[174:177], v[92:95]
	s_waitcnt vmcnt(8)
	v_lshlrev_b32_e32 v141, 16, v72
	v_mul_f32_e32 v141, v168, v141
	s_cmp_gt_u32 s13, 28
	v_mfma_f32_16x16x32_bf16 v[84:87], v[170:173], v[182:185], v[84:87]
	ds_read_b64_tr_b16 v[170:171], v165 offset:5120
	ds_read_b64_tr_b16 v[172:173], v165 offset:7680
	s_waitcnt lgkmcnt(2)
	v_mfma_f32_16x16x32_bf16 v[88:91], v[178:181], v[174:177], v[88:91]
	v_mfma_f32_16x16x32_bf16 v[80:83], v[178:181], v[182:185], v[80:83]
	ds_read_b64_tr_b16 v[174:175], v166 offset:37888
	ds_read_b64_tr_b16 v[176:177], v166 offset:46592
	ds_read_b64_tr_b16 v[178:179], v166 offset:37920
	ds_read_b64_tr_b16 v[180:181], v166 offset:46624
	ds_read_b64_tr_b16 v[182:183], v165 offset:5152
	ds_read_b64_tr_b16 v[184:185], v165 offset:7712
	s_waitcnt lgkmcnt(4)
	v_mfma_f32_16x16x32_bf16 v[108:111], v[170:173], v[174:177], v[108:111]
	s_waitcnt lgkmcnt(2)
	v_mfma_f32_16x16x32_bf16 v[104:107], v[170:173], v[178:181], v[104:107]
	ds_read_b64_tr_b16 v[170:171], v165 offset:5184
	ds_read_b64_tr_b16 v[172:173], v165 offset:7744
	s_waitcnt lgkmcnt(2)
	v_mfma_f32_16x16x32_bf16 v[100:103], v[182:185], v[174:177], v[100:103]
	v_mfma_f32_16x16x32_bf16 v[96:99], v[182:185], v[178:181], v[96:99]
	ds_read_b64_tr_b16 v[184:185], v165 offset:7776
	ds_read_b64_tr_b16 v[182:183], v165 offset:5216
	s_waitcnt lgkmcnt(2)
	v_mfma_f32_16x16x32_bf16 v[92:95], v[170:173], v[174:177], v[92:95]
	v_mfma_f32_16x16x32_bf16 v[84:87], v[170:173], v[178:181], v[84:87]
	ds_read_b64_tr_b16 v[170:171], v165 offset:10240
	ds_read_b64_tr_b16 v[172:173], v165 offset:12800
	s_waitcnt lgkmcnt(2)
	v_mfma_f32_16x16x32_bf16 v[88:91], v[182:185], v[174:177], v[88:91]
	v_mfma_f32_16x16x32_bf16 v[80:83], v[182:185], v[178:181], v[80:83]
	ds_read_b64_tr_b16 v[174:175], v166 offset:55296
	ds_read_b64_tr_b16 v[176:177], v166 offset:64000
	ds_read_b64_tr_b16 v[178:179], v166 offset:55328
	ds_read_b64_tr_b16 v[180:181], v166 offset:64032
	ds_read_b64_tr_b16 v[182:183], v165 offset:10272
	ds_read_b64_tr_b16 v[184:185], v165 offset:12832
	s_waitcnt lgkmcnt(4)
	v_mfma_f32_16x16x32_bf16 v[108:111], v[170:173], v[174:177], v[108:111]
	s_waitcnt lgkmcnt(2)
	v_mfma_f32_16x16x32_bf16 v[104:107], v[170:173], v[178:181], v[104:107]
	ds_read_b64_tr_b16 v[170:171], v165 offset:10304
	ds_read_b64_tr_b16 v[172:173], v165 offset:12864
	s_waitcnt lgkmcnt(2)
	v_mfma_f32_16x16x32_bf16 v[100:103], v[182:185], v[174:177], v[100:103]
	v_mfma_f32_16x16x32_bf16 v[96:99], v[182:185], v[178:181], v[96:99]
	ds_read_b64_tr_b16 v[184:185], v165 offset:12896
	ds_read_b64_tr_b16 v[182:183], v165 offset:10336
	s_waitcnt lgkmcnt(2)
	v_mfma_f32_16x16x32_bf16 v[92:95], v[170:173], v[174:177], v[92:95]
	v_mfma_f32_16x16x32_bf16 v[84:87], v[170:173], v[178:181], v[84:87]
	ds_read_b64_tr_b16 v[170:171], v165 offset:15360
	ds_read_b64_tr_b16 v[172:173], v165 offset:17920
	s_waitcnt lgkmcnt(2)
	v_mfma_f32_16x16x32_bf16 v[88:91], v[182:185], v[174:177], v[88:91]
	v_mfma_f32_16x16x32_bf16 v[174:177], v[182:185], v[178:181], v[80:83]
	ds_read_b64_tr_b16 v[180:181], v167 offset:64000
	ds_read_b64_tr_b16 v[178:179], v167 offset:55296
	ds_read_b64_tr_b16 v[182:183], v167 offset:55328
	ds_read_b64_tr_b16 v[184:185], v167 offset:64032
	ds_read_b64_tr_b16 v[80:81], v165 offset:15392
	v_and_b32_e32 v148, 0xffff0000, v72
	v_mul_f32_e32 v148, v168, v148
	s_waitcnt lgkmcnt(3)
	v_mfma_f32_16x16x32_bf16 v[108:111], v[170:173], v[178:181], v[108:111]
	ds_read_b64_tr_b16 v[82:83], v165 offset:17952
	ds_read_b64_tr_b16 v[188:189], v165 offset:18016
	v_and_b32_e32 v149, 0xffff0000, v73
	s_waitcnt lgkmcnt(3)
	v_mfma_f32_16x16x32_bf16 v[104:107], v[170:173], v[182:185], v[104:107]
	ds_read_b64_tr_b16 v[170:171], v165 offset:15424
	ds_read_b64_tr_b16 v[172:173], v165 offset:17984
	ds_read_b64_tr_b16 v[186:187], v165 offset:15456
	s_waitcnt lgkmcnt(0)
	s_barrier
	ds_write_b128 v155, v[24:27] offset:20480
	ds_write_b128 v156, v[28:31] offset:20480
	ds_write_b128 v157, v[40:43] offset:20480
	ds_write_b128 v158, v[44:47] offset:20480
	ds_write_b128 v159, v[56:59] offset:20480
	ds_write_b128 v160, v[60:63] offset:20480
	ds_write_b128 v161, v[64:67] offset:20480
	ds_write_b128 v162, v[68:71] offset:20480
	v_cvt_pk_bf16_f32 v148, v141, v148
	v_lshlrev_b32_e32 v141, 16, v73
	v_mul_f32_e32 v141, v168, v141
	v_mul_f32_e32 v149, v168, v149
	v_cvt_pk_bf16_f32 v149, v141, v149
	v_lshlrev_b32_e32 v141, 16, v74
	v_and_b32_e32 v150, 0xffff0000, v74
	v_mul_f32_e32 v141, v168, v141
	v_mul_f32_e32 v150, v168, v150
	v_cvt_pk_bf16_f32 v150, v141, v150
	v_lshlrev_b32_e32 v141, 16, v75
	v_and_b32_e32 v151, 0xffff0000, v75
	v_mul_f32_e32 v141, v168, v141
	v_mul_f32_e32 v151, v168, v151
	v_cvt_pk_bf16_f32 v151, v141, v151
	ds_write_b128 v163, v[148:151]
	s_waitcnt vmcnt(8)
	v_lshlrev_b32_e32 v141, 16, v76
	v_and_b32_e32 v148, 0xffff0000, v76
	v_mul_f32_e32 v141, v169, v141
	v_mul_f32_e32 v148, v169, v148
	v_cvt_pk_bf16_f32 v148, v141, v148
	v_lshlrev_b32_e32 v141, 16, v77
	v_and_b32_e32 v149, 0xffff0000, v77
	v_mfma_f32_16x16x32_bf16 v[100:103], v[80:83], v[178:181], v[100:103]
	v_mul_f32_e32 v141, v169, v141
	v_mul_f32_e32 v149, v169, v149
	v_cvt_pk_bf16_f32 v149, v141, v149
	v_mfma_f32_16x16x32_bf16 v[96:99], v[80:83], v[182:185], v[96:99]
	v_lshlrev_b32_e32 v141, 16, v78
	v_and_b32_e32 v150, 0xffff0000, v78
	v_mul_f32_e32 v141, v169, v141
	v_mfma_f32_16x16x32_bf16 v[92:95], v[170:173], v[178:181], v[92:95]
	v_mul_f32_e32 v150, v169, v150
	v_and_b32_e32 v151, 0xffff0000, v79
	v_cvt_pk_bf16_f32 v150, v141, v150
	v_mfma_f32_16x16x32_bf16 v[80:83], v[170:173], v[182:185], v[84:87]
	v_lshlrev_b32_e32 v141, 16, v79
	v_mul_f32_e32 v151, v169, v151
	v_mul_f32_e32 v141, v169, v141
	v_mfma_f32_16x16x32_bf16 v[88:91], v[186:189], v[178:181], v[88:91]
	v_cvt_pk_bf16_f32 v151, v141, v151
	ds_write_b128 v164, v[148:151]
	s_waitcnt lgkmcnt(0)
	v_mfma_f32_16x16x32_bf16 v[84:87], v[186:189], v[182:185], v[174:177]
	s_barrier
	s_cbranch_scc1 .LBB0_227
	s_and_b64 s[42:43], s[4:5], exec
	s_cselect_b32 s41, s40, s12
	s_mul_i32 s80, s41, 0x1d0000
	s_lshl_b64 s[42:43], s[80:81], 1
	s_add_u32 s42, s9, s42
	s_addc_u32 s43, s14, s43
	v_lshl_add_u64 v[24:25], s[42:43], 0, v[114:115]
	v_lshl_add_u64 v[24:25], v[24:25], 0, v[192:193]
	v_add_co_u32_e32 v24, vcc, s65, v24
	v_lshl_add_u64 v[26:27], s[42:43], 0, v[116:117]
	s_nop 0
	v_addc_co_u32_e32 v25, vcc, 0, v25, vcc
	v_lshl_add_u64 v[26:27], v[26:27], 0, v[192:193]
	v_add_co_u32_e32 v28, vcc, s65, v26
	v_lshl_add_u64 v[40:41], s[42:43], 0, v[118:119]
	s_nop 0
	v_addc_co_u32_e32 v29, vcc, 0, v27, vcc
	v_lshl_add_u64 v[40:41], v[40:41], 0, v[192:193]
	v_add_co_u32_e32 v40, vcc, s65, v40
	v_lshl_add_u64 v[42:43], s[42:43], 0, v[120:121]
	s_nop 0
	v_addc_co_u32_e32 v41, vcc, 0, v41, vcc
	v_lshl_add_u64 v[42:43], v[42:43], 0, v[192:193]
	v_add_co_u32_e32 v44, vcc, s65, v42
	v_lshl_add_u64 v[56:57], s[42:43], 0, v[122:123]
	s_nop 0
	v_addc_co_u32_e32 v45, vcc, 0, v43, vcc
	v_lshl_add_u64 v[56:57], v[56:57], 0, v[192:193]
	v_add_co_u32_e32 v56, vcc, s65, v56
	v_lshl_add_u64 v[58:59], s[42:43], 0, v[124:125]
	s_nop 0
	v_addc_co_u32_e32 v57, vcc, 0, v57, vcc
	v_lshl_add_u64 v[58:59], v[58:59], 0, v[192:193]
	v_add_co_u32_e32 v60, vcc, s65, v58
	v_lshl_add_u64 v[64:65], s[42:43], 0, v[126:127]
	s_nop 0
	v_addc_co_u32_e32 v61, vcc, 0, v59, vcc
	v_lshl_add_u64 v[64:65], v[64:65], 0, v[192:193]
	v_add_co_u32_e32 v64, vcc, s65, v64
	v_lshl_add_u64 v[66:67], s[42:43], 0, v[128:129]
	s_nop 0
	v_addc_co_u32_e32 v65, vcc, 0, v65, vcc
	v_lshl_add_u64 v[66:67], v[66:67], 0, v[192:193]
	v_lshl_add_u64 v[72:73], s[42:43], 0, v[132:133]
	s_lshl_b32 s80, s15, 1
	v_lshl_add_u64 v[74:75], s[42:43], 0, v[134:135]
	v_add_co_u32_e32 v68, vcc, s65, v66
	v_lshl_add_u64 v[72:73], v[72:73], 0, s[80:81]
	v_mov_b32_e32 v141, v193
	v_lshl_add_u64 v[74:75], v[74:75], 0, s[80:81]
	v_addc_co_u32_e32 v69, vcc, 0, v67, vcc
	v_lshl_add_u64 v[72:73], v[72:73], 0, v[140:141]
	v_lshl_add_u64 v[76:77], v[74:75], 0, v[140:141]
	global_load_dwordx4 v[24:27], v[24:25], off
	s_nop 0
	global_load_dwordx4 v[28:31], v[28:29], off
	s_nop 0
	global_load_dwordx4 v[40:43], v[40:41], off
	s_nop 0
	global_load_dwordx4 v[44:47], v[44:45], off
	s_nop 0
	global_load_dwordx4 v[56:59], v[56:57], off
	s_nop 0
	global_load_dwordx4 v[60:63], v[60:61], off
	s_nop 0
	global_load_dwordx4 v[64:67], v[64:65], off
	s_nop 0
	global_load_dwordx4 v[68:71], v[68:69], off
	s_nop 0
	global_load_dwordx4 v[72:75], v[72:73], off offset:2048
	s_nop 0
	global_load_dwordx4 v[76:79], v[76:77], off offset:2048
	s_branch .LBB0_227

; #define PG8_STAGE(bufoff, gbase, voff) do { _Pragma("unroll") for (int _i = 0; _i < 2; ++_i) \
;         __builtin_amdgcn_global_load_lds((const unsigned*)((const char*)(gbase) + (voff)[_i]), (LAS unsigned*)(lds + (bufoff) + ldsw + _i * 8192), 16, 0, 0); } while (0)
; #define PG8_LDA(dst, b, h) do { _Pragma("unroll") for (int m = 0; m < 4; ++m) _Pragma("unroll") for (int k = 0; k < 2; ++k) dst[m][k] = *(const LAS bf16x8*)(lds + PG8_SA(b, h) + aoff + m * 2048 + k * 1024); } while (0)
; #define PG8_LDB(dst, b, h) do { _Pragma("unroll") for (int n = 0; n < 2; ++n) _Pragma("unroll") for (int k = 0; k < 2; ++k) dst[n][k] = *(const LAS bf16x8*)(lds + PG8_SB(b, h) + boff + n * 2048 + k * 1024); } while (0)
; #define PG8_MMA(ai, bj, At, Bt) do { __builtin_amdgcn_s_setprio(1); _Pragma("unroll") for (int m = 0; m < 4; ++m) _Pragma("unroll") for (int n = 0; n < 2; ++n) _Pragma("unroll") for (int k = 0; k < 2; ++k) \
;         acc[ai][bj][m][n] = __builtin_amdgcn_mfma_f32_16x16x32_bf16(Bt[n][k], At[m][k], acc[ai][bj][m][n], 0, 0, 0); __builtin_amdgcn_s_setprio(0); } while (0)
; #define PG8_BAR __builtin_amdgcn_s_barrier()
; template <class Prog>
; __device__ __forceinline__ void gemm_phase(LAS unsigned char* lds, const int K, const Prog& S) {
;     ...
;     for (;;) {
;         const bool has_next = S.next(ui + 1, nxt);
;         const char* nA = has_next ? nxt.a : cA; const char* nB = has_next ? nxt.b : cB;
;         for (int t = 0; t < nt; t += 2) {
;             const bool last = (t == nt - 2);
;             const char* a1 = cA + (size_t)(t + 1) * kstep;
;             const char* a2 = last ? nA : cA + (size_t)(t + 2) * kstep; const char* b2 = last ? nB : cB + (size_t)(t + 2) * kstep;
;             const char* a3 = a2 + kstep; const char* b3 = b2 + kstep;
;             PG8_LDB(B0, 0, 0); PG8_SCHED; PG8_LDA(At, 0, 0); PG8_STAGE(PG8_SA(1, 1), a1 + hstep, voffA);
;             PG8_WAIT_L(8); PG8_BAR; PG8_WAIT_L(0); PG8_MMA(0, 0, At, B0); PG8_BAR; PG8_SCHED;
;             PG8_LDB(B1, 0, 1); PG8_STAGE(PG8_SB(0, 0), b2, voffB);
;             PG8_BAR; PG8_WAIT_L(0); PG8_MMA(0, 1, At, B1); PG8_BAR;
;             PG8_LDA(At, 0, 1); PG8_STAGE(PG8_SA(0, 0), a2, voffA);
;             PG8_BAR; PG8_WAIT_L(0); PG8_MMA(1, 0, At, B0); PG8_BAR; PG8_SCHED;
;             PG8_STAGE(PG8_SB(0, 1), b2 + hstep, voffB);
;             PG8_WAIT_V(6); PG8_BAR; PG8_MMA(1, 1, At, B1); PG8_BAR;
.LBB0_400:
	s_add_u32 s46, s44, 0xfffc0080
	s_addc_u32 s47, s45, -1
	s_cmp_eq_u32 s55, 12
	s_cselect_b32 s53, s7, s47
	s_cselect_b32 s52, s6, s46
	s_cselect_b32 s47, s9, s43
	s_cselect_b32 s46, s8, s41
	s_add_u32 s84, s44, 0xfffc0000
	s_addc_u32 s85, s45, -1
	v_add_u32_e32 v140, 0x10000, v245
	ds_read_b128 v[128:131], v140
	ds_read_b128 v[132:135], v140 offset:1024
	ds_read_b128 v[136:139], v140 offset:2048
	ds_read_b128 v[140:143], v140 offset:3072
	v_lshl_add_u64 v[206:207], s[84:85], 0, v[202:203]
	s_add_i32 m0, s74, 0x8000
	v_add_u32_e32 v188, 0x14000, v245
	ds_read_b128 v[176:179], v188
	ds_read_b128 v[180:183], v188 offset:1024
	ds_read_b128 v[184:187], v188 offset:2048
	ds_read_b128 v[188:191], v188 offset:3072
	global_load_lds_dwordx4 v[206:207], off
	v_lshl_add_u64 v[208:209], s[84:85], 0, v[204:205]
	s_add_i32 m0, s74, 0xa000
	ds_read_b128 v[144:147], v247
	ds_read_b128 v[148:151], v247 offset:1024
	ds_read_b128 v[152:155], v247 offset:2048
	ds_read_b128 v[156:159], v247 offset:3072
	global_load_lds_dwordx4 v[208:209], off
	v_lshl_add_u64 v[210:211], s[44:45], 0, v[202:203]
	s_add_i32 m0, s74, 0xc000
	ds_read_b128 v[160:163], v247 offset:4096
	ds_read_b128 v[164:167], v247 offset:5120
	ds_read_b128 v[168:171], v247 offset:6144
	ds_read_b128 v[172:175], v247 offset:7168
	global_load_lds_dwordx4 v[210:211], off
	v_lshl_add_u64 v[212:213], s[44:45], 0, v[204:205]
	s_add_i32 m0, s74, 0xe000
	s_nop 0
	global_load_lds_dwordx4 v[212:213], off
	s_waitcnt lgkmcnt(0)
	s_barrier
	s_setprio 1
	v_mfma_f32_16x16x32_bf16 v[124:127], v[128:131], v[144:147], v[124:127]
	v_mfma_f32_16x16x32_bf16 v[120:123], v[136:139], v[144:147], v[120:123]
	v_mfma_f32_16x16x32_bf16 v[116:119], v[128:131], v[152:155], v[116:119]
	v_mfma_f32_16x16x32_bf16 v[112:115], v[136:139], v[152:155], v[112:115]
	v_mfma_f32_16x16x32_bf16 v[108:111], v[128:131], v[160:163], v[108:111]
	v_mfma_f32_16x16x32_bf16 v[104:107], v[136:139], v[160:163], v[104:107]
	v_mfma_f32_16x16x32_bf16 v[100:103], v[128:131], v[168:171], v[100:103]
	v_mfma_f32_16x16x32_bf16 v[96:99], v[136:139], v[168:171], v[96:99]
	v_mfma_f32_16x16x32_bf16 v[124:127], v[132:135], v[148:151], v[124:127]
	v_mfma_f32_16x16x32_bf16 v[120:123], v[140:143], v[148:151], v[120:123]
	v_mfma_f32_16x16x32_bf16 v[116:119], v[132:135], v[156:159], v[116:119]
	v_mfma_f32_16x16x32_bf16 v[112:115], v[140:143], v[156:159], v[112:115]
	v_mfma_f32_16x16x32_bf16 v[108:111], v[132:135], v[164:167], v[108:111]
	v_mfma_f32_16x16x32_bf16 v[104:107], v[140:143], v[164:167], v[104:107]
	v_mfma_f32_16x16x32_bf16 v[100:103], v[132:135], v[172:175], v[100:103]
	v_mfma_f32_16x16x32_bf16 v[96:99], v[140:143], v[172:175], v[96:99]
	v_mfma_f32_16x16x32_bf16 v[92:95], v[176:179], v[144:147], v[92:95]
	v_mfma_f32_16x16x32_bf16 v[88:91], v[184:187], v[144:147], v[88:91]
	v_mfma_f32_16x16x32_bf16 v[84:87], v[176:179], v[152:155], v[84:87]
	v_mfma_f32_16x16x32_bf16 v[80:83], v[184:187], v[152:155], v[80:83]
	v_mfma_f32_16x16x32_bf16 v[76:79], v[176:179], v[160:163], v[76:79]
	v_mfma_f32_16x16x32_bf16 v[72:75], v[184:187], v[160:163], v[72:75]
	v_mfma_f32_16x16x32_bf16 v[68:71], v[176:179], v[168:171], v[68:71]
	v_mfma_f32_16x16x32_bf16 v[64:67], v[184:187], v[168:171], v[64:67]
	v_mfma_f32_16x16x32_bf16 v[92:95], v[180:183], v[148:151], v[92:95]
	v_mfma_f32_16x16x32_bf16 v[88:91], v[188:191], v[148:151], v[88:91]
	v_mfma_f32_16x16x32_bf16 v[84:87], v[180:183], v[156:159], v[84:87]
	v_mfma_f32_16x16x32_bf16 v[80:83], v[188:191], v[156:159], v[80:83]
	v_mfma_f32_16x16x32_bf16 v[76:79], v[180:183], v[164:167], v[76:79]
	v_mfma_f32_16x16x32_bf16 v[72:75], v[188:191], v[164:167], v[72:75]
	v_mfma_f32_16x16x32_bf16 v[68:71], v[180:183], v[172:175], v[68:71]
	v_mfma_f32_16x16x32_bf16 v[64:67], v[188:191], v[172:175], v[64:67]
	s_setprio 0
	s_barrier
	ds_read_b128 v[144:147], v247 offset:16384
	ds_read_b128 v[148:151], v247 offset:17408
	ds_read_b128 v[152:155], v247 offset:18432
	ds_read_b128 v[156:159], v247 offset:19456
	v_lshl_add_u64 v[206:207], s[46:47], 0, v[192:193]
	s_add_i32 m0, s74, 0x10000
	ds_read_b128 v[160:163], v247 offset:20480
	ds_read_b128 v[164:167], v247 offset:21504
	ds_read_b128 v[168:171], v247 offset:22528
	ds_read_b128 v[172:175], v247 offset:23552
	global_load_lds_dwordx4 v[206:207], off
	v_lshl_add_u64 v[208:209], s[46:47], 0, v[200:201]
	s_add_i32 m0, s74, 0x12000
	s_nop 0
	global_load_lds_dwordx4 v[208:209], off
	s_add_u32 s84, s46, 0x40000
	s_addc_u32 s85, s47, 0
	v_lshl_add_u64 v[210:211], s[84:85], 0, v[192:193]
	s_add_i32 m0, s74, 0x14000
	s_nop 0
	global_load_lds_dwordx4 v[210:211], off
	v_lshl_add_u64 v[212:213], s[84:85], 0, v[200:201]
	s_add_i32 m0, s74, 0x16000
	s_nop 0
	global_load_lds_dwordx4 v[212:213], off
	s_waitcnt vmcnt(4)
	s_waitcnt lgkmcnt(0)
	s_barrier
; #define PG8_STAGE(bufoff, gbase, voff) do { _Pragma("unroll") for (int _i = 0; _i < 2; ++_i) \
;         __builtin_amdgcn_global_load_lds((const unsigned*)((const char*)(gbase) + (voff)[_i]), (LAS unsigned*)(lds + (bufoff) + ldsw + _i * 8192), 16, 0, 0); } while (0)
; #define PG8_LDA(dst, b, h) do { _Pragma("unroll") for (int m = 0; m < 4; ++m) _Pragma("unroll") for (int k = 0; k < 2; ++k) dst[m][k] = *(const LAS bf16x8*)(lds + PG8_SA(b, h) + aoff + m * 2048 + k * 1024); } while (0)
; #define PG8_LDB(dst, b, h) do { _Pragma("unroll") for (int n = 0; n < 2; ++n) _Pragma("unroll") for (int k = 0; k < 2; ++k) dst[n][k] = *(const LAS bf16x8*)(lds + PG8_SB(b, h) + boff + n * 2048 + k * 1024); } while (0)
; #define PG8_MMA(ai, bj, At, Bt) do { __builtin_amdgcn_s_setprio(1); _Pragma("unroll") for (int m = 0; m < 4; ++m) _Pragma("unroll") for (int n = 0; n < 2; ++n) _Pragma("unroll") for (int k = 0; k < 2; ++k) \
;         acc[ai][bj][m][n] = __builtin_amdgcn_mfma_f32_16x16x32_bf16(Bt[n][k], At[m][k], acc[ai][bj][m][n], 0, 0, 0); __builtin_amdgcn_s_setprio(0); } while (0)
; #define PG8_WAIT_V(n) asm volatile("s_waitcnt vmcnt(" #n ")" ::: "memory")
; #define PG8_WAIT_L(n) asm volatile("s_waitcnt lgkmcnt(" #n ")" ::: "memory")
; #define PG8_BAR __builtin_amdgcn_s_barrier()
; #define PG8_SCHED __builtin_amdgcn_sched_barrier(0)
; template <class Prog>
; __device__ __forceinline__ void gemm_phase(LAS unsigned char* lds, const int K, const Prog& S) {
;     ...
;             PG8_WAIT_V(6); PG8_BAR; PG8_MMA(1, 1, At, B1); PG8_BAR;
;             PG8_LDB(B0, 1, 0); PG8_SCHED; PG8_LDA(At, 1, 0); PG8_STAGE(PG8_SA(0, 1), a2 + hstep, voffA);
;             PG8_WAIT_L(8); PG8_BAR; PG8_WAIT_L(0); PG8_MMA(0, 0, At, B0); PG8_BAR; PG8_SCHED;
;             PG8_LDB(B1, 1, 1); PG8_STAGE(PG8_SB(1, 0), b3, voffB);
;             PG8_BAR; PG8_WAIT_L(0); PG8_MMA(0, 1, At, B1); PG8_BAR;
	s_setprio 1
	v_mfma_f32_16x16x32_bf16 v[60:63], v[128:131], v[144:147], v[60:63]
	v_mfma_f32_16x16x32_bf16 v[56:59], v[136:139], v[144:147], v[56:59]
	v_mfma_f32_16x16x32_bf16 v[52:55], v[128:131], v[152:155], v[52:55]
	v_mfma_f32_16x16x32_bf16 v[48:51], v[136:139], v[152:155], v[48:51]
	v_mfma_f32_16x16x32_bf16 v[44:47], v[128:131], v[160:163], v[44:47]
	v_mfma_f32_16x16x32_bf16 v[40:43], v[136:139], v[160:163], v[40:43]
	v_mfma_f32_16x16x32_bf16 v[36:39], v[128:131], v[168:171], v[36:39]
	v_mfma_f32_16x16x32_bf16 v[32:35], v[136:139], v[168:171], v[32:35]
	v_mfma_f32_16x16x32_bf16 v[60:63], v[132:135], v[148:151], v[60:63]
	v_mfma_f32_16x16x32_bf16 v[56:59], v[140:143], v[148:151], v[56:59]
	v_mfma_f32_16x16x32_bf16 v[52:55], v[132:135], v[156:159], v[52:55]
	v_mfma_f32_16x16x32_bf16 v[48:51], v[140:143], v[156:159], v[48:51]
	v_mfma_f32_16x16x32_bf16 v[44:47], v[132:135], v[164:167], v[44:47]
	v_mfma_f32_16x16x32_bf16 v[40:43], v[140:143], v[164:167], v[40:43]
	v_mfma_f32_16x16x32_bf16 v[36:39], v[132:135], v[172:175], v[36:39]
	v_mfma_f32_16x16x32_bf16 v[32:35], v[140:143], v[172:175], v[32:35]
	v_mfma_f32_16x16x32_bf16 v[28:31], v[176:179], v[144:147], v[28:31]
	v_mfma_f32_16x16x32_bf16 v[24:27], v[184:187], v[144:147], v[24:27]
	v_mfma_f32_16x16x32_bf16 v[20:23], v[176:179], v[152:155], v[20:23]
	v_mfma_f32_16x16x32_bf16 v[16:19], v[184:187], v[152:155], v[16:19]
	v_mfma_f32_16x16x32_bf16 v[12:15], v[176:179], v[160:163], v[12:15]
	v_mfma_f32_16x16x32_bf16 v[8:11], v[184:187], v[160:163], v[8:11]
	v_mfma_f32_16x16x32_bf16 v[4:7], v[176:179], v[168:171], v[4:7]
	v_mfma_f32_16x16x32_bf16 v[0:3], v[184:187], v[168:171], v[0:3]
	v_mfma_f32_16x16x32_bf16 v[28:31], v[180:183], v[148:151], v[28:31]
	v_mfma_f32_16x16x32_bf16 v[24:27], v[188:191], v[148:151], v[24:27]
	v_mfma_f32_16x16x32_bf16 v[20:23], v[180:183], v[156:159], v[20:23]
	v_mfma_f32_16x16x32_bf16 v[16:19], v[188:191], v[156:159], v[16:19]
	v_mfma_f32_16x16x32_bf16 v[12:15], v[180:183], v[164:167], v[12:15]
	v_mfma_f32_16x16x32_bf16 v[8:11], v[188:191], v[164:167], v[8:11]
	v_mfma_f32_16x16x32_bf16 v[4:7], v[180:183], v[172:175], v[4:7]
	v_mfma_f32_16x16x32_bf16 v[0:3], v[188:191], v[172:175], v[0:3]
	s_setprio 0
	s_barrier
	s_add_u32 s84, s52, 0x40000
	s_addc_u32 s85, s53, 0
	v_add_u32_e32 v140, 0x18000, v245
	ds_read_b128 v[128:131], v140
	ds_read_b128 v[132:135], v140 offset:1024
	ds_read_b128 v[136:139], v140 offset:2048
	ds_read_b128 v[140:143], v140 offset:3072
	v_lshl_add_u64 v[206:207], s[52:53], 0, v[196:197]
	s_mov_b32 m0, s74
	v_add_u32_e32 v188, 0x1c000, v245
	ds_read_b128 v[176:179], v188
	ds_read_b128 v[180:183], v188 offset:1024
	ds_read_b128 v[184:187], v188 offset:2048
	ds_read_b128 v[188:191], v188 offset:3072
	global_load_lds_dwordx4 v[206:207], off
	v_lshl_add_u64 v[208:209], s[52:53], 0, v[198:199]
	s_add_i32 m0, s74, 0x2000
	ds_read_b128 v[144:147], v247 offset:32768
	ds_read_b128 v[148:151], v247 offset:33792
	ds_read_b128 v[152:155], v247 offset:34816
	ds_read_b128 v[156:159], v247 offset:35840
	global_load_lds_dwordx4 v[208:209], off
	v_lshl_add_u64 v[210:211], s[84:85], 0, v[196:197]
	s_add_i32 m0, s74, 0x4000
	ds_read_b128 v[160:163], v247 offset:36864
	ds_read_b128 v[164:167], v247 offset:37888
	ds_read_b128 v[168:171], v247 offset:38912
	ds_read_b128 v[172:175], v247 offset:39936
	global_load_lds_dwordx4 v[210:211], off
	v_lshl_add_u64 v[212:213], s[84:85], 0, v[198:199]
	s_add_i32 m0, s74, 0x6000
	s_nop 0
	global_load_lds_dwordx4 v[212:213], off
	s_waitcnt lgkmcnt(0)
	s_barrier
	s_setprio 1
	v_mfma_f32_16x16x32_bf16 v[124:127], v[128:131], v[144:147], v[124:127]
	v_mfma_f32_16x16x32_bf16 v[120:123], v[136:139], v[144:147], v[120:123]
	v_mfma_f32_16x16x32_bf16 v[116:119], v[128:131], v[152:155], v[116:119]
	v_mfma_f32_16x16x32_bf16 v[112:115], v[136:139], v[152:155], v[112:115]
	v_mfma_f32_16x16x32_bf16 v[108:111], v[128:131], v[160:163], v[108:111]
	v_mfma_f32_16x16x32_bf16 v[104:107], v[136:139], v[160:163], v[104:107]
	v_mfma_f32_16x16x32_bf16 v[100:103], v[128:131], v[168:171], v[100:103]
	v_mfma_f32_16x16x32_bf16 v[96:99], v[136:139], v[168:171], v[96:99]
	v_mfma_f32_16x16x32_bf16 v[124:127], v[132:135], v[148:151], v[124:127]
	v_mfma_f32_16x16x32_bf16 v[120:123], v[140:143], v[148:151], v[120:123]
	v_mfma_f32_16x16x32_bf16 v[116:119], v[132:135], v[156:159], v[116:119]
	v_mfma_f32_16x16x32_bf16 v[112:115], v[140:143], v[156:159], v[112:115]
	v_mfma_f32_16x16x32_bf16 v[108:111], v[132:135], v[164:167], v[108:111]
	v_mfma_f32_16x16x32_bf16 v[104:107], v[140:143], v[164:167], v[104:107]
	v_mfma_f32_16x16x32_bf16 v[100:103], v[132:135], v[172:175], v[100:103]
	v_mfma_f32_16x16x32_bf16 v[96:99], v[140:143], v[172:175], v[96:99]
	v_mfma_f32_16x16x32_bf16 v[92:95], v[176:179], v[144:147], v[92:95]
	v_mfma_f32_16x16x32_bf16 v[88:91], v[184:187], v[144:147], v[88:91]
	v_mfma_f32_16x16x32_bf16 v[84:87], v[176:179], v[152:155], v[84:87]
	v_mfma_f32_16x16x32_bf16 v[80:83], v[184:187], v[152:155], v[80:83]
	v_mfma_f32_16x16x32_bf16 v[76:79], v[176:179], v[160:163], v[76:79]
	v_mfma_f32_16x16x32_bf16 v[72:75], v[184:187], v[160:163], v[72:75]
	v_mfma_f32_16x16x32_bf16 v[68:71], v[176:179], v[168:171], v[68:71]
	v_mfma_f32_16x16x32_bf16 v[64:67], v[184:187], v[168:171], v[64:67]
	v_mfma_f32_16x16x32_bf16 v[92:95], v[180:183], v[148:151], v[92:95]
	v_mfma_f32_16x16x32_bf16 v[88:91], v[188:191], v[148:151], v[88:91]
	v_mfma_f32_16x16x32_bf16 v[84:87], v[180:183], v[156:159], v[84:87]
	v_mfma_f32_16x16x32_bf16 v[80:83], v[188:191], v[156:159], v[80:83]
	v_mfma_f32_16x16x32_bf16 v[76:79], v[180:183], v[164:167], v[76:79]
	v_mfma_f32_16x16x32_bf16 v[72:75], v[188:191], v[164:167], v[72:75]
	v_mfma_f32_16x16x32_bf16 v[68:71], v[180:183], v[172:175], v[68:71]
	v_mfma_f32_16x16x32_bf16 v[64:67], v[188:191], v[172:175], v[64:67]
	s_setprio 0
	s_barrier
; #define PG8_STAGE(bufoff, gbase, voff) do { _Pragma("unroll") for (int _i = 0; _i < 2; ++_i) \
;         __builtin_amdgcn_global_load_lds((const unsigned*)((const char*)(gbase) + (voff)[_i]), (LAS unsigned*)(lds + (bufoff) + ldsw + _i * 8192), 16, 0, 0); } while (0)
; #define PG8_LDA(dst, b, h) do { _Pragma("unroll") for (int m = 0; m < 4; ++m) _Pragma("unroll") for (int k = 0; k < 2; ++k) dst[m][k] = *(const LAS bf16x8*)(lds + PG8_SA(b, h) + aoff + m * 2048 + k * 1024); } while (0)
; #define PG8_MMA(ai, bj, At, Bt) do { __builtin_amdgcn_s_setprio(1); _Pragma("unroll") for (int m = 0; m < 4; ++m) _Pragma("unroll") for (int n = 0; n < 2; ++n) _Pragma("unroll") for (int k = 0; k < 2; ++k) \
;         acc[ai][bj][m][n] = __builtin_amdgcn_mfma_f32_16x16x32_bf16(Bt[n][k], At[m][k], acc[ai][bj][m][n], 0, 0, 0); __builtin_amdgcn_s_setprio(0); } while (0)
; #define PG8_WAIT_V(n) asm volatile("s_waitcnt vmcnt(" #n ")" ::: "memory")
; #define PG8_WAIT_L(n) asm volatile("s_waitcnt lgkmcnt(" #n ")" ::: "memory")
; #define PG8_BAR __builtin_amdgcn_s_barrier()
; #define PG8_SCHED __builtin_amdgcn_sched_barrier(0)
; template <class Prog>
; __device__ __forceinline__ void gemm_phase(LAS unsigned char* lds, const int K, const Prog& S) {
;     ...
;             PG8_LDA(At, 1, 1); PG8_STAGE(PG8_SA(1, 0), a3, voffA);
;             PG8_BAR; PG8_WAIT_L(0); PG8_MMA(1, 0, At, B0); PG8_BAR; PG8_SCHED;
;             PG8_STAGE(PG8_SB(1, 1), b3 + hstep, voffB);
;             PG8_WAIT_V(6); PG8_BAR; PG8_MMA(1, 1, At, B1); PG8_BAR;
;         }
;         S.epi(acc, cur, wr, wc, fr, fq);
;     __device__ __forceinline__ void epi(f32x4 (&acc)[2][2][4][2], const pg8::Unit& u, int wr, int wc, int fr, int fq) const {
;     ...
;         const int dsub = sub < 2 ? sub + 1 : sub;
	s_add_u32 s84, s46, 0x80
	s_addc_u32 s85, s47, 0
	ds_read_b128 v[144:147], v247 offset:49152
	ds_read_b128 v[148:151], v247 offset:50176
	ds_read_b128 v[152:155], v247 offset:51200
	ds_read_b128 v[156:159], v247 offset:52224
	v_lshl_add_u64 v[206:207], s[84:85], 0, v[192:193]
	s_add_i32 m0, s74, 0x18000
	ds_read_b128 v[160:163], v247 offset:53248
	ds_read_b128 v[164:167], v247 offset:54272
	ds_read_b128 v[168:171], v247 offset:55296
	ds_read_b128 v[172:175], v247 offset:56320
	global_load_lds_dwordx4 v[206:207], off
	v_lshl_add_u64 v[208:209], s[84:85], 0, v[200:201]
	s_add_i32 m0, s74, 0x1a000
	s_nop 0
	global_load_lds_dwordx4 v[208:209], off
	s_add_u32 s84, s46, 0x40080
	s_addc_u32 s85, s47, 0
	v_lshl_add_u64 v[210:211], s[84:85], 0, v[192:193]
	s_add_i32 m0, s74, 0x1c000
	s_nop 0
	global_load_lds_dwordx4 v[210:211], off
	v_lshl_add_u64 v[212:213], s[84:85], 0, v[200:201]
	s_add_i32 m0, s74, 0x1e000
	s_nop 0
	global_load_lds_dwordx4 v[212:213], off
	s_waitcnt vmcnt(4)
	s_waitcnt lgkmcnt(0)
	s_barrier
	s_setprio 1
	v_mfma_f32_16x16x32_bf16 v[60:63], v[128:131], v[144:147], v[60:63]
	v_mfma_f32_16x16x32_bf16 v[56:59], v[136:139], v[144:147], v[56:59]
	v_mfma_f32_16x16x32_bf16 v[52:55], v[128:131], v[152:155], v[52:55]
	v_mfma_f32_16x16x32_bf16 v[48:51], v[136:139], v[152:155], v[48:51]
	v_mfma_f32_16x16x32_bf16 v[44:47], v[128:131], v[160:163], v[44:47]
	v_mfma_f32_16x16x32_bf16 v[40:43], v[136:139], v[160:163], v[40:43]
	v_mfma_f32_16x16x32_bf16 v[36:39], v[128:131], v[168:171], v[36:39]
	v_mfma_f32_16x16x32_bf16 v[32:35], v[136:139], v[168:171], v[32:35]
	v_mfma_f32_16x16x32_bf16 v[60:63], v[132:135], v[148:151], v[60:63]
	v_mfma_f32_16x16x32_bf16 v[56:59], v[140:143], v[148:151], v[56:59]
	v_mfma_f32_16x16x32_bf16 v[52:55], v[132:135], v[156:159], v[52:55]
	v_mfma_f32_16x16x32_bf16 v[48:51], v[140:143], v[156:159], v[48:51]
	v_mfma_f32_16x16x32_bf16 v[44:47], v[132:135], v[164:167], v[44:47]
	v_mfma_f32_16x16x32_bf16 v[40:43], v[140:143], v[164:167], v[40:43]
	v_mfma_f32_16x16x32_bf16 v[36:39], v[132:135], v[172:175], v[36:39]
	v_mfma_f32_16x16x32_bf16 v[32:35], v[140:143], v[172:175], v[32:35]
	v_mfma_f32_16x16x32_bf16 v[28:31], v[176:179], v[144:147], v[28:31]
	v_mfma_f32_16x16x32_bf16 v[24:27], v[184:187], v[144:147], v[24:27]
	v_mfma_f32_16x16x32_bf16 v[20:23], v[176:179], v[152:155], v[20:23]
	v_mfma_f32_16x16x32_bf16 v[16:19], v[184:187], v[152:155], v[16:19]
	v_mfma_f32_16x16x32_bf16 v[12:15], v[176:179], v[160:163], v[12:15]
	v_mfma_f32_16x16x32_bf16 v[8:11], v[184:187], v[160:163], v[8:11]
	v_mfma_f32_16x16x32_bf16 v[4:7], v[176:179], v[168:171], v[4:7]
	v_mfma_f32_16x16x32_bf16 v[0:3], v[184:187], v[168:171], v[0:3]
	v_mfma_f32_16x16x32_bf16 v[28:31], v[180:183], v[148:151], v[28:31]
	v_mfma_f32_16x16x32_bf16 v[24:27], v[188:191], v[148:151], v[24:27]
	v_mfma_f32_16x16x32_bf16 v[20:23], v[180:183], v[156:159], v[20:23]
	v_mfma_f32_16x16x32_bf16 v[16:19], v[188:191], v[156:159], v[16:19]
	v_mfma_f32_16x16x32_bf16 v[12:15], v[180:183], v[164:167], v[12:15]
	v_mfma_f32_16x16x32_bf16 v[8:11], v[188:191], v[164:167], v[8:11]
	v_mfma_f32_16x16x32_bf16 v[4:7], v[180:183], v[172:175], v[4:7]
	v_mfma_f32_16x16x32_bf16 v[0:3], v[188:191], v[172:175], v[0:3]
	s_setprio 0
	s_add_i32 s55, s55, 2
	s_add_u32 s44, s44, 0x100
	s_addc_u32 s45, s45, 0
	s_add_u32 s41, s41, 0x100
	s_addc_u32 s43, s43, 0
	s_cmp_gt_u32 s55, 13
	s_barrier
	s_cbranch_scc0 .LBB0_400
	s_cmp_lt_i32 s14, 2
	v_lshl_add_u32 v208, s15, 8, v244
	v_lshl_or_b32 v206, s54, 8, v246
	s_cselect_b64 s[8:9], -1, 0
	s_cmp_gt_i32 s14, 1
	v_mov_b64_e32 v[128:129], s[26:27]
	s_cselect_b64 s[92:93], -1, 0
	s_cmp_lg_u64 s[8:9], 0
	v_ashrrev_i32_e32 v207, 31, v206
	v_mad_i64_i32 v[128:129], s[6:7], v208, s58, v[128:129]
	s_addc_u32 s15, s14, 0
	s_lshl_b32 s46, s14, 11
	v_lshl_add_u64 v[128:129], v[206:207], 1, v[128:129]
	s_ashr_i32 s47, s46, 31
	v_lshl_add_u64 v[128:129], v[128:129], 0, s[34:35]
	v_lshl_add_u64 v[130:131], s[46:47], 1, v[128:129]
	global_load_dwordx4 v[188:191], v[130:131], off
	s_lshl_b32 s52, s15, 11
	s_ashr_i32 s53, s52, 31
	v_mov_b32_e32 v148, 0
	s_and_b64 vcc, exec, s[92:93]
	v_lshl_add_u64 v[128:129], s[52:53], 1, v[128:129]
	v_mov_b32_e32 v180, 0
	v_mov_b32_e32 v181, 0
	v_mov_b32_e32 v182, 0
	v_mov_b32_e32 v183, 0
	s_cbranch_vccnz .LBB0_403
	global_load_dwordx4 v[180:183], v[128:129], off

; #define PG8_STAGE(bufoff, gbase, voff) do { _Pragma("unroll") for (int _i = 0; _i < 2; ++_i) \
;         __builtin_amdgcn_global_load_lds((const unsigned*)((const char*)(gbase) + (voff)[_i]), (LAS unsigned*)(lds + (bufoff) + ldsw + _i * 8192), 16, 0, 0); } while (0)
; #define PG8_LDA(dst, b, h) do { _Pragma("unroll") for (int m = 0; m < 4; ++m) _Pragma("unroll") for (int k = 0; k < 2; ++k) dst[m][k] = *(const LAS bf16x8*)(lds + PG8_SA(b, h) + aoff + m * 2048 + k * 1024); } while (0)
; #define PG8_WAIT_V(n) asm volatile("s_waitcnt vmcnt(" #n ")" ::: "memory")
; #define PG8_WAIT_L(n) asm volatile("s_waitcnt lgkmcnt(" #n ")" ::: "memory")
; template <class Prog>
; __device__ __forceinline__ void gemm_phase(LAS unsigned char* lds, const int K, const Prog& S) {
;     ...
;     Unit cur, nxt; int ui = 0;
;     if (!S.next(0, cur)) return;
;     f32x4 acc[2][2][4][2];
; #pragma unroll
;     for (int a = 0; a < 2; ++a)
; #pragma unroll
;         for (int b = 0; b < 2; ++b)
; #pragma unroll
;             for (int m = 0; m < 4; ++m)
; #pragma unroll
;                 for (int n = 0; n < 2; ++n) acc[a][b][m][n] = (f32x4){0.f, 0.f, 0.f, 0.f};
;     bf16x8 At[4][2], B0[2][2], B1[2][2];
;     const char* cA = cur.a; const char* cB = cur.b;
;     PG8_STAGE(PG8_SB(0, 0), cB, voffB); PG8_STAGE(PG8_SA(0, 0), cA, voffA); PG8_STAGE(PG8_SB(0, 1), cB + hstep, voffB); PG8_STAGE(PG8_SA(0, 1), cA + hstep, voffA);
;     if (wr == 1) PG8_BAR;
;     PG8_WAIT_V(4); PG8_BAR;
;     PG8_STAGE(PG8_SB(1, 0), cB + kstep, voffB); PG8_STAGE(PG8_SA(1, 0), cA + kstep, voffA); PG8_STAGE(PG8_SB(1, 1), cB + hstep + kstep, voffB);
;     PG8_WAIT_V(6); PG8_BAR;
;     for (;;) {
;         const bool has_next = S.next(ui + 1, nxt);
;         const char* nA = has_next ? nxt.a : cA; const char* nB = has_next ? nxt.b : cB;
;         for (int t = 0; t < nt; t += 2) {
;             const bool last = (t == nt - 2);
;             const char* a1 = cA + (size_t)(t + 1) * kstep;
;             const char* a2 = last ? nA : cA + (size_t)(t + 2) * kstep; const char* b2 = last ? nB : cB + (size_t)(t + 2) * kstep;
;             const char* a3 = a2 + kstep; const char* b3 = b2 + kstep;
;             PG8_LDB(B0, 0, 0); PG8_SCHED; PG8_LDA(At, 0, 0); PG8_STAGE(PG8_SA(1, 1), a1 + hstep, voffA);
;             PG8_WAIT_L(8); PG8_BAR; PG8_WAIT_L(0); PG8_MMA(0, 0, At, B0); PG8_BAR; PG8_SCHED;
.LBB0_570:
	s_add_u32 s46, s46, 0x80080
	s_addc_u32 s47, s47, 0
	s_add_u32 s41, s52, 0x100
	v_mov_b32_e32 v0, 0
	s_addc_u32 s43, s53, 0
	s_mov_b32 s54, -2
	s_waitcnt lgkmcnt(0)
	v_mov_b32_e32 v1, v0
	v_mov_b32_e32 v2, v0
	v_mov_b32_e32 v3, v0
	v_mov_b32_e32 v4, v0
	v_mov_b32_e32 v5, v0
	v_mov_b32_e32 v6, v0
	v_mov_b32_e32 v7, v0
	v_mov_b32_e32 v16, v0
	v_mov_b32_e32 v17, v0
	v_mov_b32_e32 v18, v0
	v_mov_b32_e32 v19, v0
	v_mov_b32_e32 v20, v0
	v_mov_b32_e32 v21, v0
	v_mov_b32_e32 v22, v0
	v_mov_b32_e32 v23, v0
	v_mov_b32_e32 v32, v0
	v_mov_b32_e32 v33, v0
	v_mov_b32_e32 v34, v0
	v_mov_b32_e32 v35, v0
	v_mov_b32_e32 v36, v0
	v_mov_b32_e32 v37, v0
	v_mov_b32_e32 v38, v0
	v_mov_b32_e32 v39, v0
	v_mov_b32_e32 v48, v0
	v_mov_b32_e32 v49, v0
	v_mov_b32_e32 v50, v0
	v_mov_b32_e32 v51, v0
	v_mov_b32_e32 v52, v0
	v_mov_b32_e32 v53, v0
	v_mov_b32_e32 v54, v0
	v_mov_b32_e32 v55, v0
	v_mov_b32_e32 v8, v0
	v_mov_b32_e32 v9, v0
	v_mov_b32_e32 v10, v0
	v_mov_b32_e32 v11, v0
	v_mov_b32_e32 v12, v0
	v_mov_b32_e32 v13, v0
	v_mov_b32_e32 v14, v0
	v_mov_b32_e32 v15, v0
	s_waitcnt vmcnt(16)
	v_mov_b32_e32 v24, v0
	v_mov_b32_e32 v25, v0
	v_mov_b32_e32 v26, v0
	v_mov_b32_e32 v27, v0
	v_mov_b32_e32 v28, v0
	v_mov_b32_e32 v29, v0
	v_mov_b32_e32 v30, v0
	v_mov_b32_e32 v31, v0
	v_mov_b32_e32 v40, v0
	v_mov_b32_e32 v41, v0
	v_mov_b32_e32 v42, v0
	v_mov_b32_e32 v43, v0
	v_mov_b32_e32 v44, v0
	v_mov_b32_e32 v45, v0
	v_mov_b32_e32 v46, v0
	v_mov_b32_e32 v47, v0
	v_mov_b32_e32 v56, v0
	v_mov_b32_e32 v57, v0
	v_mov_b32_e32 v58, v0
	v_mov_b32_e32 v59, v0
	v_mov_b32_e32 v60, v0
	v_mov_b32_e32 v61, v0
	v_mov_b32_e32 v62, v0
	v_mov_b32_e32 v63, v0
	v_mov_b32_e32 v64, v0
	v_mov_b32_e32 v65, v0
	v_mov_b32_e32 v66, v0
	v_mov_b32_e32 v67, v0
	v_mov_b32_e32 v68, v0
	v_mov_b32_e32 v69, v0
	v_mov_b32_e32 v70, v0
	v_mov_b32_e32 v71, v0
	v_mov_b32_e32 v80, v0
	v_mov_b32_e32 v81, v0
	v_mov_b32_e32 v82, v0
	v_mov_b32_e32 v83, v0
	v_mov_b32_e32 v84, v0
	v_mov_b32_e32 v85, v0
	v_mov_b32_e32 v86, v0
	v_mov_b32_e32 v87, v0
	v_mov_b32_e32 v96, v0
	v_mov_b32_e32 v97, v0
	v_mov_b32_e32 v98, v0
	v_mov_b32_e32 v99, v0
	v_mov_b32_e32 v100, v0
	v_mov_b32_e32 v101, v0
	v_mov_b32_e32 v102, v0
	v_mov_b32_e32 v103, v0
	v_mov_b32_e32 v112, v0
	v_mov_b32_e32 v113, v0
	v_mov_b32_e32 v114, v0
	v_mov_b32_e32 v115, v0
	v_mov_b32_e32 v116, v0
	v_mov_b32_e32 v117, v0
	v_mov_b32_e32 v118, v0
	v_mov_b32_e32 v119, v0
	v_mov_b32_e32 v72, v0
	v_mov_b32_e32 v73, v0
	v_mov_b32_e32 v74, v0
	v_mov_b32_e32 v75, v0
	v_mov_b32_e32 v76, v0
	v_mov_b32_e32 v77, v0
	v_mov_b32_e32 v78, v0
	v_mov_b32_e32 v79, v0
	v_mov_b32_e32 v88, v0
	v_mov_b32_e32 v89, v0
	v_mov_b32_e32 v90, v0
	v_mov_b32_e32 v91, v0
	v_mov_b32_e32 v92, v0
	v_mov_b32_e32 v93, v0
	v_mov_b32_e32 v94, v0
	v_mov_b32_e32 v95, v0
	v_mov_b32_e32 v104, v0
	v_mov_b32_e32 v105, v0
	v_mov_b32_e32 v106, v0
	v_mov_b32_e32 v107, v0
	v_mov_b32_e32 v108, v0
	v_mov_b32_e32 v109, v0
	v_mov_b32_e32 v110, v0
	v_mov_b32_e32 v111, v0
	v_mov_b32_e32 v120, v0
	v_mov_b32_e32 v121, v0
	v_mov_b32_e32 v122, v0
	v_mov_b32_e32 v123, v0
	v_mov_b32_e32 v124, v0
	v_mov_b32_e32 v125, v0
	v_mov_b32_e32 v126, v0
	v_mov_b32_e32 v127, v0
.LBB0_571:
	s_add_u32 s52, s46, 0xfff80080
	s_addc_u32 s53, s47, -1
	s_cmp_eq_u32 s54, 28
	s_cselect_b32 s93, s7, s53
	s_cselect_b32 s92, s6, s52
	s_cselect_b32 s53, s45, s43
	s_cselect_b32 s52, s44, s41
	s_add_u32 vcc_lo, s46, 0xfff80000
	s_addc_u32 vcc_hi, s47, -1
	v_add_u32_e32 v140, 0x10000, v215
	ds_read_b128 v[128:131], v140
	ds_read_b128 v[132:135], v140 offset:1024
	ds_read_b128 v[136:139], v140 offset:2048
	ds_read_b128 v[140:143], v140 offset:3072
	v_lshl_add_u64 v[202:203], vcc, 0, v[190:191]
	s_add_i32 m0, s75, 0x8000
	v_add_u32_e32 v198, 0x14000, v215
	ds_read_b128 v[176:179], v198
	ds_read_b128 v[180:183], v198 offset:1024
	ds_read_b128 v[184:187], v198 offset:2048
	ds_read_b128 v[198:201], v198 offset:3072
	global_load_lds_dwordx4 v[202:203], off
	v_lshl_add_u64 v[204:205], vcc, 0, v[196:197]
	s_add_i32 m0, s75, 0xa000
	ds_read_b128 v[144:147], v217
	ds_read_b128 v[148:151], v217 offset:1024
	ds_read_b128 v[152:155], v217 offset:2048
	ds_read_b128 v[156:159], v217 offset:3072
	global_load_lds_dwordx4 v[204:205], off
	v_lshl_add_u64 v[206:207], s[46:47], 0, v[190:191]
	s_add_i32 m0, s75, 0xc000
	ds_read_b128 v[160:163], v217 offset:4096
	ds_read_b128 v[164:167], v217 offset:5120
	ds_read_b128 v[168:171], v217 offset:6144
	ds_read_b128 v[172:175], v217 offset:7168
	global_load_lds_dwordx4 v[206:207], off
	v_lshl_add_u64 v[208:209], s[46:47], 0, v[196:197]
	s_add_i32 m0, s75, 0xe000
	s_nop 0
	global_load_lds_dwordx4 v[208:209], off
	s_waitcnt lgkmcnt(0)
	s_barrier
; #define PG8_STAGE(bufoff, gbase, voff) do { _Pragma("unroll") for (int _i = 0; _i < 2; ++_i) \
;         __builtin_amdgcn_global_load_lds((const unsigned*)((const char*)(gbase) + (voff)[_i]), (LAS unsigned*)(lds + (bufoff) + ldsw + _i * 8192), 16, 0, 0); } while (0)
; #define PG8_LDA(dst, b, h) do { _Pragma("unroll") for (int m = 0; m < 4; ++m) _Pragma("unroll") for (int k = 0; k < 2; ++k) dst[m][k] = *(const LAS bf16x8*)(lds + PG8_SA(b, h) + aoff + m * 2048 + k * 1024); } while (0)
; #define PG8_LDB(dst, b, h) do { _Pragma("unroll") for (int n = 0; n < 2; ++n) _Pragma("unroll") for (int k = 0; k < 2; ++k) dst[n][k] = *(const LAS bf16x8*)(lds + PG8_SB(b, h) + boff + n * 2048 + k * 1024); } while (0)
; #define PG8_MMA(ai, bj, At, Bt) do { __builtin_amdgcn_s_setprio(1); _Pragma("unroll") for (int m = 0; m < 4; ++m) _Pragma("unroll") for (int n = 0; n < 2; ++n) _Pragma("unroll") for (int k = 0; k < 2; ++k) \
;         acc[ai][bj][m][n] = __builtin_amdgcn_mfma_f32_16x16x32_bf16(Bt[n][k], At[m][k], acc[ai][bj][m][n], 0, 0, 0); __builtin_amdgcn_s_setprio(0); } while (0)
; #define PG8_WAIT_V(n) asm volatile("s_waitcnt vmcnt(" #n ")" ::: "memory")
; #define PG8_WAIT_L(n) asm volatile("s_waitcnt lgkmcnt(" #n ")" ::: "memory")
; #define PG8_BAR __builtin_amdgcn_s_barrier()
; #define PG8_SCHED __builtin_amdgcn_sched_barrier(0)
; template <class Prog>
; __device__ __forceinline__ void gemm_phase(LAS unsigned char* lds, const int K, const Prog& S) {
;     ...
;             PG8_WAIT_L(8); PG8_BAR; PG8_WAIT_L(0); PG8_MMA(0, 0, At, B0); PG8_BAR; PG8_SCHED;
;             PG8_LDB(B1, 0, 1); PG8_STAGE(PG8_SB(0, 0), b2, voffB);
;             PG8_BAR; PG8_WAIT_L(0); PG8_MMA(0, 1, At, B1); PG8_BAR;
;             PG8_LDA(At, 0, 1); PG8_STAGE(PG8_SA(0, 0), a2, voffA);
;             PG8_BAR; PG8_WAIT_L(0); PG8_MMA(1, 0, At, B0); PG8_BAR; PG8_SCHED;
;             PG8_STAGE(PG8_SB(0, 1), b2 + hstep, voffB);
;             PG8_WAIT_V(6); PG8_BAR; PG8_MMA(1, 1, At, B1); PG8_BAR;
	s_setprio 1
	v_mfma_f32_16x16x32_bf16 v[124:127], v[128:131], v[144:147], v[124:127]
	v_mfma_f32_16x16x32_bf16 v[120:123], v[136:139], v[144:147], v[120:123]
	v_mfma_f32_16x16x32_bf16 v[108:111], v[128:131], v[152:155], v[108:111]
	v_mfma_f32_16x16x32_bf16 v[104:107], v[136:139], v[152:155], v[104:107]
	v_mfma_f32_16x16x32_bf16 v[92:95], v[128:131], v[160:163], v[92:95]
	v_mfma_f32_16x16x32_bf16 v[88:91], v[136:139], v[160:163], v[88:91]
	v_mfma_f32_16x16x32_bf16 v[76:79], v[128:131], v[168:171], v[76:79]
	v_mfma_f32_16x16x32_bf16 v[72:75], v[136:139], v[168:171], v[72:75]
	v_mfma_f32_16x16x32_bf16 v[124:127], v[132:135], v[148:151], v[124:127]
	v_mfma_f32_16x16x32_bf16 v[120:123], v[140:143], v[148:151], v[120:123]
	v_mfma_f32_16x16x32_bf16 v[108:111], v[132:135], v[156:159], v[108:111]
	v_mfma_f32_16x16x32_bf16 v[104:107], v[140:143], v[156:159], v[104:107]
	v_mfma_f32_16x16x32_bf16 v[92:95], v[132:135], v[164:167], v[92:95]
	v_mfma_f32_16x16x32_bf16 v[88:91], v[140:143], v[164:167], v[88:91]
	v_mfma_f32_16x16x32_bf16 v[76:79], v[132:135], v[172:175], v[76:79]
	v_mfma_f32_16x16x32_bf16 v[72:75], v[140:143], v[172:175], v[72:75]
	v_mfma_f32_16x16x32_bf16 v[116:119], v[176:179], v[144:147], v[116:119]
	v_mfma_f32_16x16x32_bf16 v[112:115], v[184:187], v[144:147], v[112:115]
	v_mfma_f32_16x16x32_bf16 v[100:103], v[176:179], v[152:155], v[100:103]
	v_mfma_f32_16x16x32_bf16 v[96:99], v[184:187], v[152:155], v[96:99]
	v_mfma_f32_16x16x32_bf16 v[84:87], v[176:179], v[160:163], v[84:87]
	v_mfma_f32_16x16x32_bf16 v[80:83], v[184:187], v[160:163], v[80:83]
	v_mfma_f32_16x16x32_bf16 v[68:71], v[176:179], v[168:171], v[68:71]
	v_mfma_f32_16x16x32_bf16 v[64:67], v[184:187], v[168:171], v[64:67]
	v_mfma_f32_16x16x32_bf16 v[116:119], v[180:183], v[148:151], v[116:119]
	v_mfma_f32_16x16x32_bf16 v[112:115], v[198:201], v[148:151], v[112:115]
	v_mfma_f32_16x16x32_bf16 v[100:103], v[180:183], v[156:159], v[100:103]
	v_mfma_f32_16x16x32_bf16 v[96:99], v[198:201], v[156:159], v[96:99]
	v_mfma_f32_16x16x32_bf16 v[84:87], v[180:183], v[164:167], v[84:87]
	v_mfma_f32_16x16x32_bf16 v[80:83], v[198:201], v[164:167], v[80:83]
	v_mfma_f32_16x16x32_bf16 v[68:71], v[180:183], v[172:175], v[68:71]
	v_mfma_f32_16x16x32_bf16 v[64:67], v[198:201], v[172:175], v[64:67]
	s_setprio 0
	s_barrier
	ds_read_b128 v[144:147], v217 offset:16384
	ds_read_b128 v[148:151], v217 offset:17408
	ds_read_b128 v[152:155], v217 offset:18432
	ds_read_b128 v[156:159], v217 offset:19456
	v_lshl_add_u64 v[202:203], s[52:53], 0, v[192:193]
	s_add_i32 m0, s75, 0x10000
	ds_read_b128 v[160:163], v217 offset:20480
	ds_read_b128 v[164:167], v217 offset:21504
	ds_read_b128 v[168:171], v217 offset:22528
	ds_read_b128 v[172:175], v217 offset:23552
	global_load_lds_dwordx4 v[202:203], off
	v_lshl_add_u64 v[204:205], s[52:53], 0, v[188:189]
	s_add_i32 m0, s75, 0x12000
	s_nop 0
	global_load_lds_dwordx4 v[204:205], off
	s_add_u32 vcc_lo, s52, 0x80000
	s_addc_u32 vcc_hi, s53, 0
	v_lshl_add_u64 v[206:207], vcc, 0, v[192:193]
	s_add_i32 m0, s75, 0x14000
	s_nop 0
	global_load_lds_dwordx4 v[206:207], off
	v_lshl_add_u64 v[208:209], vcc, 0, v[188:189]
	s_add_i32 m0, s75, 0x16000
	s_nop 0
	global_load_lds_dwordx4 v[208:209], off
	s_waitcnt vmcnt(4)
	s_waitcnt lgkmcnt(0)
	s_barrier
	s_setprio 1
	v_mfma_f32_16x16x32_bf16 v[60:63], v[128:131], v[144:147], v[60:63]
	v_mfma_f32_16x16x32_bf16 v[56:59], v[136:139], v[144:147], v[56:59]
	v_mfma_f32_16x16x32_bf16 v[44:47], v[128:131], v[152:155], v[44:47]
	v_mfma_f32_16x16x32_bf16 v[40:43], v[136:139], v[152:155], v[40:43]
	v_mfma_f32_16x16x32_bf16 v[28:31], v[128:131], v[160:163], v[28:31]
	v_mfma_f32_16x16x32_bf16 v[24:27], v[136:139], v[160:163], v[24:27]
	v_mfma_f32_16x16x32_bf16 v[12:15], v[128:131], v[168:171], v[12:15]
	v_mfma_f32_16x16x32_bf16 v[8:11], v[136:139], v[168:171], v[8:11]
	v_mfma_f32_16x16x32_bf16 v[60:63], v[132:135], v[148:151], v[60:63]
	v_mfma_f32_16x16x32_bf16 v[56:59], v[140:143], v[148:151], v[56:59]
	v_mfma_f32_16x16x32_bf16 v[44:47], v[132:135], v[156:159], v[44:47]
	v_mfma_f32_16x16x32_bf16 v[40:43], v[140:143], v[156:159], v[40:43]
	v_mfma_f32_16x16x32_bf16 v[28:31], v[132:135], v[164:167], v[28:31]
	v_mfma_f32_16x16x32_bf16 v[24:27], v[140:143], v[164:167], v[24:27]
	v_mfma_f32_16x16x32_bf16 v[12:15], v[132:135], v[172:175], v[12:15]
	v_mfma_f32_16x16x32_bf16 v[8:11], v[140:143], v[172:175], v[8:11]
	v_mfma_f32_16x16x32_bf16 v[52:55], v[176:179], v[144:147], v[52:55]
	v_mfma_f32_16x16x32_bf16 v[48:51], v[184:187], v[144:147], v[48:51]
	v_mfma_f32_16x16x32_bf16 v[36:39], v[176:179], v[152:155], v[36:39]
	v_mfma_f32_16x16x32_bf16 v[32:35], v[184:187], v[152:155], v[32:35]
	v_mfma_f32_16x16x32_bf16 v[20:23], v[176:179], v[160:163], v[20:23]
	v_mfma_f32_16x16x32_bf16 v[16:19], v[184:187], v[160:163], v[16:19]
	v_mfma_f32_16x16x32_bf16 v[4:7], v[176:179], v[168:171], v[4:7]
	v_mfma_f32_16x16x32_bf16 v[0:3], v[184:187], v[168:171], v[0:3]
	v_mfma_f32_16x16x32_bf16 v[52:55], v[180:183], v[148:151], v[52:55]
	v_mfma_f32_16x16x32_bf16 v[48:51], v[198:201], v[148:151], v[48:51]
	v_mfma_f32_16x16x32_bf16 v[36:39], v[180:183], v[156:159], v[36:39]
	v_mfma_f32_16x16x32_bf16 v[32:35], v[198:201], v[156:159], v[32:35]
	v_mfma_f32_16x16x32_bf16 v[20:23], v[180:183], v[164:167], v[20:23]
	v_mfma_f32_16x16x32_bf16 v[16:19], v[198:201], v[164:167], v[16:19]
	v_mfma_f32_16x16x32_bf16 v[4:7], v[180:183], v[172:175], v[4:7]
	v_mfma_f32_16x16x32_bf16 v[0:3], v[198:201], v[172:175], v[0:3]
	s_setprio 0
	s_barrier
; #define PG8_STAGE(bufoff, gbase, voff) do { _Pragma("unroll") for (int _i = 0; _i < 2; ++_i) \
;         __builtin_amdgcn_global_load_lds((const unsigned*)((const char*)(gbase) + (voff)[_i]), (LAS unsigned*)(lds + (bufoff) + ldsw + _i * 8192), 16, 0, 0); } while (0)
; #define PG8_LDA(dst, b, h) do { _Pragma("unroll") for (int m = 0; m < 4; ++m) _Pragma("unroll") for (int k = 0; k < 2; ++k) dst[m][k] = *(const LAS bf16x8*)(lds + PG8_SA(b, h) + aoff + m * 2048 + k * 1024); } while (0)
; #define PG8_LDB(dst, b, h) do { _Pragma("unroll") for (int n = 0; n < 2; ++n) _Pragma("unroll") for (int k = 0; k < 2; ++k) dst[n][k] = *(const LAS bf16x8*)(lds + PG8_SB(b, h) + boff + n * 2048 + k * 1024); } while (0)
; #define PG8_MMA(ai, bj, At, Bt) do { __builtin_amdgcn_s_setprio(1); _Pragma("unroll") for (int m = 0; m < 4; ++m) _Pragma("unroll") for (int n = 0; n < 2; ++n) _Pragma("unroll") for (int k = 0; k < 2; ++k) \
;         acc[ai][bj][m][n] = __builtin_amdgcn_mfma_f32_16x16x32_bf16(Bt[n][k], At[m][k], acc[ai][bj][m][n], 0, 0, 0); __builtin_amdgcn_s_setprio(0); } while (0)
; #define PG8_WAIT_L(n) asm volatile("s_waitcnt lgkmcnt(" #n ")" ::: "memory")
; #define PG8_BAR __builtin_amdgcn_s_barrier()
; #define PG8_SCHED __builtin_amdgcn_sched_barrier(0)
; template <class Prog>
; __device__ __forceinline__ void gemm_phase(LAS unsigned char* lds, const int K, const Prog& S) {
;     ...
;             PG8_LDB(B0, 1, 0); PG8_SCHED; PG8_LDA(At, 1, 0); PG8_STAGE(PG8_SA(0, 1), a2 + hstep, voffA);
;             PG8_WAIT_L(8); PG8_BAR; PG8_WAIT_L(0); PG8_MMA(0, 0, At, B0); PG8_BAR; PG8_SCHED;
;             PG8_LDB(B1, 1, 1); PG8_STAGE(PG8_SB(1, 0), b3, voffB);
;             PG8_BAR; PG8_WAIT_L(0); PG8_MMA(0, 1, At, B1); PG8_BAR;
;             PG8_LDA(At, 1, 1); PG8_STAGE(PG8_SA(1, 0), a3, voffA);
;             PG8_BAR; PG8_WAIT_L(0); PG8_MMA(1, 0, At, B0); PG8_BAR; PG8_SCHED;
	s_add_u32 vcc_lo, s92, 0x80000
	s_addc_u32 vcc_hi, s93, 0
	v_add_u32_e32 v140, 0x18000, v215
	ds_read_b128 v[128:131], v140
	ds_read_b128 v[132:135], v140 offset:1024
	ds_read_b128 v[136:139], v140 offset:2048
	ds_read_b128 v[140:143], v140 offset:3072
	v_lshl_add_u64 v[202:203], s[92:93], 0, v[192:193]
	s_mov_b32 m0, s75
	v_add_u32_e32 v198, 0x1c000, v215
	ds_read_b128 v[176:179], v198
	ds_read_b128 v[180:183], v198 offset:1024
	ds_read_b128 v[184:187], v198 offset:2048
	ds_read_b128 v[198:201], v198 offset:3072
	global_load_lds_dwordx4 v[202:203], off
	v_lshl_add_u64 v[204:205], s[92:93], 0, v[188:189]
	s_add_i32 m0, s75, 0x2000
	ds_read_b128 v[144:147], v217 offset:32768
	ds_read_b128 v[148:151], v217 offset:33792
	ds_read_b128 v[152:155], v217 offset:34816
	ds_read_b128 v[156:159], v217 offset:35840
	global_load_lds_dwordx4 v[204:205], off
	v_lshl_add_u64 v[206:207], vcc, 0, v[192:193]
	s_add_i32 m0, s75, 0x4000
	ds_read_b128 v[160:163], v217 offset:36864
	ds_read_b128 v[164:167], v217 offset:37888
	ds_read_b128 v[168:171], v217 offset:38912
	ds_read_b128 v[172:175], v217 offset:39936
	global_load_lds_dwordx4 v[206:207], off
	v_lshl_add_u64 v[208:209], vcc, 0, v[188:189]
	s_add_i32 m0, s75, 0x6000
	s_nop 0
	global_load_lds_dwordx4 v[208:209], off
	s_waitcnt lgkmcnt(0)
	s_barrier
	s_setprio 1
	v_mfma_f32_16x16x32_bf16 v[124:127], v[128:131], v[144:147], v[124:127]
	v_mfma_f32_16x16x32_bf16 v[120:123], v[136:139], v[144:147], v[120:123]
	v_mfma_f32_16x16x32_bf16 v[108:111], v[128:131], v[152:155], v[108:111]
	v_mfma_f32_16x16x32_bf16 v[104:107], v[136:139], v[152:155], v[104:107]
	v_mfma_f32_16x16x32_bf16 v[92:95], v[128:131], v[160:163], v[92:95]
	v_mfma_f32_16x16x32_bf16 v[88:91], v[136:139], v[160:163], v[88:91]
	v_mfma_f32_16x16x32_bf16 v[76:79], v[128:131], v[168:171], v[76:79]
	v_mfma_f32_16x16x32_bf16 v[72:75], v[136:139], v[168:171], v[72:75]
	v_mfma_f32_16x16x32_bf16 v[124:127], v[132:135], v[148:151], v[124:127]
	v_mfma_f32_16x16x32_bf16 v[120:123], v[140:143], v[148:151], v[120:123]
	v_mfma_f32_16x16x32_bf16 v[108:111], v[132:135], v[156:159], v[108:111]
	v_mfma_f32_16x16x32_bf16 v[104:107], v[140:143], v[156:159], v[104:107]
	v_mfma_f32_16x16x32_bf16 v[92:95], v[132:135], v[164:167], v[92:95]
	v_mfma_f32_16x16x32_bf16 v[88:91], v[140:143], v[164:167], v[88:91]
	v_mfma_f32_16x16x32_bf16 v[76:79], v[132:135], v[172:175], v[76:79]
	v_mfma_f32_16x16x32_bf16 v[72:75], v[140:143], v[172:175], v[72:75]
	v_mfma_f32_16x16x32_bf16 v[116:119], v[176:179], v[144:147], v[116:119]
	v_mfma_f32_16x16x32_bf16 v[112:115], v[184:187], v[144:147], v[112:115]
	v_mfma_f32_16x16x32_bf16 v[100:103], v[176:179], v[152:155], v[100:103]
	v_mfma_f32_16x16x32_bf16 v[96:99], v[184:187], v[152:155], v[96:99]
	v_mfma_f32_16x16x32_bf16 v[84:87], v[176:179], v[160:163], v[84:87]
	v_mfma_f32_16x16x32_bf16 v[80:83], v[184:187], v[160:163], v[80:83]
	v_mfma_f32_16x16x32_bf16 v[68:71], v[176:179], v[168:171], v[68:71]
	v_mfma_f32_16x16x32_bf16 v[64:67], v[184:187], v[168:171], v[64:67]
	v_mfma_f32_16x16x32_bf16 v[116:119], v[180:183], v[148:151], v[116:119]
	v_mfma_f32_16x16x32_bf16 v[112:115], v[198:201], v[148:151], v[112:115]
	v_mfma_f32_16x16x32_bf16 v[100:103], v[180:183], v[156:159], v[100:103]
	v_mfma_f32_16x16x32_bf16 v[96:99], v[198:201], v[156:159], v[96:99]
	v_mfma_f32_16x16x32_bf16 v[84:87], v[180:183], v[164:167], v[84:87]
	v_mfma_f32_16x16x32_bf16 v[80:83], v[198:201], v[164:167], v[80:83]
	v_mfma_f32_16x16x32_bf16 v[68:71], v[180:183], v[172:175], v[68:71]
	v_mfma_f32_16x16x32_bf16 v[64:67], v[198:201], v[172:175], v[64:67]
	s_setprio 0
	s_barrier
	s_add_u32 vcc_lo, s52, 0x80
	s_addc_u32 vcc_hi, s53, 0
	ds_read_b128 v[144:147], v217 offset:49152
	ds_read_b128 v[148:151], v217 offset:50176
	ds_read_b128 v[152:155], v217 offset:51200
	ds_read_b128 v[156:159], v217 offset:52224
	v_lshl_add_u64 v[202:203], vcc, 0, v[192:193]
	s_add_i32 m0, s75, 0x18000
	ds_read_b128 v[160:163], v217 offset:53248
	ds_read_b128 v[164:167], v217 offset:54272
	ds_read_b128 v[168:171], v217 offset:55296
	ds_read_b128 v[172:175], v217 offset:56320
	global_load_lds_dwordx4 v[202:203], off
	v_lshl_add_u64 v[204:205], vcc, 0, v[188:189]
	s_add_i32 m0, s75, 0x1a000
	s_nop 0
	global_load_lds_dwordx4 v[204:205], off
	s_add_u32 vcc_lo, s52, 0x80080
	s_addc_u32 vcc_hi, s53, 0
	v_lshl_add_u64 v[206:207], vcc, 0, v[192:193]
	s_add_i32 m0, s75, 0x1c000
	s_nop 0
	global_load_lds_dwordx4 v[206:207], off
	v_lshl_add_u64 v[208:209], vcc, 0, v[188:189]
	s_add_i32 m0, s75, 0x1e000
	s_nop 0
	global_load_lds_dwordx4 v[208:209], off
	s_waitcnt vmcnt(4)
	s_waitcnt lgkmcnt(0)
	s_barrier
; __device__ __forceinline__ unsigned cvt_pk_bf16(float lo, float hi) { unsigned r; asm volatile("v_cvt_pk_bf16_f32 %0, %1, %2" : "=v"(r) : "v"(lo), "v"(hi)); return r; }
; #define PG8_MMA(ai, bj, At, Bt) do { __builtin_amdgcn_s_setprio(1); _Pragma("unroll") for (int m = 0; m < 4; ++m) _Pragma("unroll") for (int n = 0; n < 2; ++n) _Pragma("unroll") for (int k = 0; k < 2; ++k) \
;         acc[ai][bj][m][n] = __builtin_amdgcn_mfma_f32_16x16x32_bf16(Bt[n][k], At[m][k], acc[ai][bj][m][n], 0, 0, 0); __builtin_amdgcn_s_setprio(0); } while (0)
; #define PG8_WAIT_V(n) asm volatile("s_waitcnt vmcnt(" #n ")" ::: "memory")
; #define PG8_BAR __builtin_amdgcn_s_barrier()
; template <class Prog>
; __device__ __forceinline__ void gemm_phase(LAS unsigned char* lds, const int K, const Prog& S) {
;     ...
;             PG8_WAIT_V(6); PG8_BAR; PG8_MMA(1, 1, At, B1); PG8_BAR;
;         }
;         S.epi(acc, cur, wr, wc, fr, fq);
;     __device__ __forceinline__ void epi(f32x4 (&acc)[2][2][4][2], const pg8::Unit& u, int wr, int wc, int fr, int fq) const {
;         const int row0 = u.pm * 256 + wr * 64 + fr, col0 = u.pn * 256 + wc * 32 + 4 * fq;
; #pragma unroll
;         for (int ai = 0; ai < 2; ++ai) {
;             f32x4 xo[4][2][2];
; #pragma unroll
;             for (int m = 0; m < 4; ++m)
; #pragma unroll
;                 for (int bj = 0; bj < 2; ++bj)
; #pragma unroll
;                     for (int n = 0; n < 2; ++n) xo[m][bj][n] = *(const f32x4*)(xin + (size_t)(row0 + ai * 128 + m * 16) * DM + col0 + bj * 128 + n * 16);
; #pragma unroll
;             for (int m = 0; m < 4; ++m) {
;                 const int row = row0 + ai * 128 + m * 16;
;                 const size_t off = (size_t)row * DM + col0;
;                 float ss = 0.f;
; #pragma unroll
;                 for (int bj = 0; bj < 2; ++bj)
; #pragma unroll
;                     for (int n = 0; n < 2; ++n) {
;                         const f32x4 o = xo[m][bj][n] + acc[ai][bj][m][n];
;                         *(f32x4*)(xout + off + bj * 128 + n * 16) = o;
;                         ss += o[0] * o[0] + o[1] * o[1] + o[2] * o[2] + o[3] * o[3];
;                         if (rowss_next) { u32x2 w; w.x = cvt_pk_bf16(o[0], o[1]); w.y = cvt_pk_bf16(o[2], o[3]); *(u32x2*)(xb + off + bj * 128 + n * 16) = w; }
	s_setprio 1
	v_mfma_f32_16x16x32_bf16 v[60:63], v[128:131], v[144:147], v[60:63]
	v_mfma_f32_16x16x32_bf16 v[56:59], v[136:139], v[144:147], v[56:59]
	v_mfma_f32_16x16x32_bf16 v[44:47], v[128:131], v[152:155], v[44:47]
	v_mfma_f32_16x16x32_bf16 v[40:43], v[136:139], v[152:155], v[40:43]
	v_mfma_f32_16x16x32_bf16 v[28:31], v[128:131], v[160:163], v[28:31]
	v_mfma_f32_16x16x32_bf16 v[24:27], v[136:139], v[160:163], v[24:27]
	v_mfma_f32_16x16x32_bf16 v[12:15], v[128:131], v[168:171], v[12:15]
	v_mfma_f32_16x16x32_bf16 v[8:11], v[136:139], v[168:171], v[8:11]
	v_mfma_f32_16x16x32_bf16 v[60:63], v[132:135], v[148:151], v[60:63]
	v_mfma_f32_16x16x32_bf16 v[56:59], v[140:143], v[148:151], v[56:59]
	v_mfma_f32_16x16x32_bf16 v[44:47], v[132:135], v[156:159], v[44:47]
	v_mfma_f32_16x16x32_bf16 v[40:43], v[140:143], v[156:159], v[40:43]
	v_mfma_f32_16x16x32_bf16 v[28:31], v[132:135], v[164:167], v[28:31]
	v_mfma_f32_16x16x32_bf16 v[24:27], v[140:143], v[164:167], v[24:27]
	v_mfma_f32_16x16x32_bf16 v[12:15], v[132:135], v[172:175], v[12:15]
	v_mfma_f32_16x16x32_bf16 v[8:11], v[140:143], v[172:175], v[8:11]
	v_mfma_f32_16x16x32_bf16 v[52:55], v[176:179], v[144:147], v[52:55]
	v_mfma_f32_16x16x32_bf16 v[48:51], v[184:187], v[144:147], v[48:51]
	v_mfma_f32_16x16x32_bf16 v[36:39], v[176:179], v[152:155], v[36:39]
	v_mfma_f32_16x16x32_bf16 v[32:35], v[184:187], v[152:155], v[32:35]
	v_mfma_f32_16x16x32_bf16 v[20:23], v[176:179], v[160:163], v[20:23]
	v_mfma_f32_16x16x32_bf16 v[16:19], v[184:187], v[160:163], v[16:19]
	v_mfma_f32_16x16x32_bf16 v[4:7], v[176:179], v[168:171], v[4:7]
	v_mfma_f32_16x16x32_bf16 v[0:3], v[184:187], v[168:171], v[0:3]
	v_mfma_f32_16x16x32_bf16 v[52:55], v[180:183], v[148:151], v[52:55]
	v_mfma_f32_16x16x32_bf16 v[48:51], v[198:201], v[148:151], v[48:51]
	v_mfma_f32_16x16x32_bf16 v[36:39], v[180:183], v[156:159], v[36:39]
	v_mfma_f32_16x16x32_bf16 v[32:35], v[198:201], v[156:159], v[32:35]
	v_mfma_f32_16x16x32_bf16 v[20:23], v[180:183], v[164:167], v[20:23]
	v_mfma_f32_16x16x32_bf16 v[16:19], v[198:201], v[164:167], v[16:19]
	v_mfma_f32_16x16x32_bf16 v[4:7], v[180:183], v[172:175], v[4:7]
	v_mfma_f32_16x16x32_bf16 v[0:3], v[198:201], v[172:175], v[0:3]
	s_setprio 0
	s_add_i32 s54, s54, 2
	s_add_u32 s46, s46, 0x100
	s_addc_u32 s47, s47, 0
	s_add_u32 s41, s41, 0x100
	s_addc_u32 s43, s43, 0
	s_cmp_gt_u32 s54, 29
	s_barrier
	s_cbranch_scc0 .LBB0_571
	v_lshl_add_u32 v202, s80, 8, v214
	v_lshl_or_b32 v198, s73, 8, v216
	v_ashrrev_i32_e32 v199, 31, v198
	v_ashrrev_i32_e32 v203, 31, v202
	v_lshl_add_u64 v[200:201], v[198:199], 2, s[8:9]
	v_lshlrev_b64 v[128:129], 13, v[202:203]
	v_or_b32_e32 v208, 16, v202
	v_lshl_add_u64 v[128:129], v[200:201], 0, v[128:129]
	v_ashrrev_i32_e32 v209, 31, v208
	global_load_dwordx4 v[210:213], v[128:129], off
	global_load_dwordx4 v[184:187], v[128:129], off offset:64
	global_load_dwordx4 v[180:183], v[128:129], off offset:512
	global_load_dwordx4 v[176:179], v[128:129], off offset:576
	v_lshlrev_b64 v[128:129], 13, v[208:209]
	v_or_b32_e32 v206, 32, v202
	v_lshl_add_u64 v[128:129], v[200:201], 0, v[128:129]
	v_ashrrev_i32_e32 v207, 31, v206
	global_load_dwordx4 v[172:175], v[128:129], off
	global_load_dwordx4 v[168:171], v[128:129], off offset:64
	global_load_dwordx4 v[164:167], v[128:129], off offset:512
	global_load_dwordx4 v[160:163], v[128:129], off offset:576
	v_lshlrev_b64 v[128:129], 13, v[206:207]
	v_or_b32_e32 v204, 48, v202
	v_lshl_add_u64 v[128:129], v[200:201], 0, v[128:129]
	v_ashrrev_i32_e32 v205, 31, v204
	global_load_dwordx4 v[156:159], v[128:129], off
	global_load_dwordx4 v[152:155], v[128:129], off offset:64
	global_load_dwordx4 v[148:151], v[128:129], off offset:512
	global_load_dwordx4 v[144:147], v[128:129], off offset:576
	v_lshlrev_b64 v[128:129], 13, v[204:205]
	v_lshl_add_u64 v[128:129], v[200:201], 0, v[128:129]
	global_load_dwordx4 v[140:143], v[128:129], off
	global_load_dwordx4 v[136:139], v[128:129], off offset:64
	global_load_dwordx4 v[132:135], v[128:129], off offset:512
	s_nop 0
	global_load_dwordx4 v[128:131], v[128:129], off offset:576
	v_lshlrev_b64 v[218:219], 11, v[202:203]
	v_lshl_add_u64 v[218:219], v[218:219], 0, v[198:199]
	s_andn2_b64 vcc, exec, s[12:13]
	s_waitcnt vmcnt(0)
	v_pk_add_f32 v[126:127], v[126:127], v[212:213]
	v_cndmask_b32_e64 v212, 0, 1, s[12:13]
	v_pk_add_f32 v[124:125], v[124:125], v[210:211]
	v_lshl_add_u64 v[210:211], v[218:219], 2, s[48:49]
	v_cmp_ne_u32_e64 s[6:7], 1, v212
	v_lshl_add_u64 v[212:213], v[218:219], 1, s[20:21]
	global_store_dwordx4 v[210:211], v[124:127], off
	s_cbranch_vccnz .LBB0_574
	v_cvt_pk_bf16_f32 v218, v124, v125
	v_cvt_pk_bf16_f32 v219, v126, v127
	global_store_dwordx2 v[212:213], v[218:219], off
